# t30 + cross-half row-max exchange via v_permlane32_swap_b32 instead of ds_bpermute (all four attention step variants); dead pad keeps loop alignment
# baseline (speedup 1.0000x reference)
; #define LAS __attribute__((address_space(3)))
; #define MFMA32(a, b, c) __builtin_amdgcn_mfma_f32_32x32x16_bf16((a), (b), (c), 0, 0, 0)
; #define WG_BAR() do { asm volatile("s_waitcnt lgkmcnt(0)" ::: "memory"); __builtin_amdgcn_s_barrier(); asm volatile("" ::: "memory"); } while (0)
; template <class ScoreFn>
; __device__ __forceinline__ void attn_step(AttnState& st, const bf16x8 (&qf)[4], LAS unsigned char* kb, LAS unsigned char* vb, int lane, const ScoreFn& sf) {
;     ...
;     LAS unsigned char* kp = kb + r * KVP; const int kx = (h ^ (r & 7)) << 4;
; #pragma unroll
;     for (int ds = 0; ds < 4; ++ds) {
;         const bf16x8 k0 = *(const LAS bf16x8*)(kp + (kx ^ (ds << 5))), k1 = *(const LAS bf16x8*)(kp + 32 * KVP + (kx ^ (ds << 5)));
;         s0 = MFMA32(k0, qf[ds], s0); s1 = MFMA32(k1, qf[ds], s1);
;     }
;     float mt = NEG_BIG;
;     __builtin_amdgcn_sched_barrier(0);
; #pragma unroll
;     for (int i = 0; i < 16; ++i) { s0[i] = sf(s0[i], (i & 3) + 8 * (i >> 2), h, r); mt = fmaxf(mt, s0[i]); if ((i & 7) == 7) __builtin_amdgcn_sched_barrier(0); }
; #pragma unroll
;     for (int i = 0; i < 16; ++i) { s1[i] = sf(s1[i], 32 + (i & 3) + 8 * (i >> 2), h, r); mt = fmaxf(mt, s1[i]); if ((i & 7) == 7) __builtin_amdgcn_sched_barrier(0); }
;     mt = fmaxf(mt, __shfl_xor(mt, 32));
;     const float mn = fmaxf(st.m, mt), alpha = __builtin_amdgcn_exp2f(st.m - mn);
;     float ps = 0.f;
; #pragma unroll
;     for (int i = 0; i < 16; ++i) { s0[i] = __builtin_amdgcn_exp2f(s0[i] - mn); s1[i] = __builtin_amdgcn_exp2f(s1[i] - mn); ps += s0[i] + s1[i]; }
; template <bool ISB>
; __device__ __forceinline__ void attn_wg_item(Frame& F, int l, int idx) {
;     ...
;     AttnState st;
; #pragma unroll
;     for (int i = 0; i < 16; ++i) { st.o0[i] = 0.f; st.o1[i] = 0.f; }
;     st.m = NEG_BIG; st.l = 0.f;
; #pragma unroll
;     for (int t = 0; t < ATT_D; ++t) ATT_DMA(t);
;     if (ISB && lat) {
;         const float* bsrc = KIN(I_NBBIAS) + (size_t)(l * 8 + (ix & 7)) * 465;
;         if (tid < 465) tab[64 + tid] = bsrc[tid] * LOG2E; }
;     for (int s = 0; s < NS; ++s) {
;         ATT_DMA(s + ATT_D);
;         asm volatile("s_waitcnt vmcnt(8)" ::: "memory");
;         WG_BAR();
;         LAS unsigned char* cur = ring + (s % ATT_NB) * KV_BUF;
.LBB0_581:
	s_mul_hi_u32 s1, s16, 0xaaaaaaab
	s_mul_hi_u32 s2, s13, 0xaaaaaaab
	s_lshr_b32 s1, s1, 2
	s_lshr_b32 s2, s2, 2
	s_mul_i32 s1, s1, 0x18000
	s_mul_i32 s2, s2, 0x18000
	v_readlane_b32 s3, v253, 15
	s_sub_i32 s1, s15, s1
	v_add3_u32 v126, s1, v104, v89
	v_add3_u32 v125, s1, v96, v89
	v_add3_u32 v127, s1, v103, v89
	v_add3_u32 v124, s1, v95, v89
	v_add3_u32 v122, s1, v102, v89
	v_add3_u32 v123, s1, v101, v89
	v_add3_u32 v119, s1, v94, v89
	v_add3_u32 v120, s1, v93, v89
	v_add3_u32 v117, s1, v100, v89
	v_add3_u32 v118, s1, v99, v89
	v_add3_u32 v115, s1, v92, v89
	v_add3_u32 v116, s1, v91, v89
	v_add3_u32 v113, s1, v98, v89
	v_add3_u32 v114, s1, v97, v89
	v_add3_u32 v111, s1, v90, v89
	v_add3_u32 v112, s1, v88, v89
	v_add_u32_e32 v128, s1, v105
	s_sub_i32 s8, s3, s2
	v_add_u32_e32 v130, s1, v106
	v_add_u32_e32 v131, s1, v107
	v_add_u32_e32 v132, s1, v108
	s_add_i32 s1, s16, 4
	s_cmp_lt_i32 s16, s11
	s_cselect_b64 s[2:3], -1, 0
	s_and_b64 vcc, s[2:3], exec
	s_cselect_b32 s1, s1, s12
	s_cmp_lt_i32 s1, s11
	s_cselect_b32 s2, 0, s11
	s_cselect_b32 s3, s10, 0x2000
	s_sub_i32 s1, s1, s2
	s_lshl_b32 s1, s1, 6
	s_add_i32 s1, s1, s3
	s_add_i32 s2, s15, s8
	v_pk_mov_b32 v[84:85], v[2:3], v[2:3] op_sel:[0,1]
	s_add_i32 s8, s2, 0
	v_mad_i64_i32 v[2:3], s[2:3], s1, v249, v[50:51]
	s_add_i32 m0, s8, 0x10000
	v_lshl_add_u64 v[4:5], v[2:3], 0, s[18:19]
	global_load_lds_dwordx4 v[4:5], off
	v_lshl_add_u64 v[2:3], v[2:3], 0, s[20:21]
	s_add_i32 m0, s8, 0x12000
	v_pk_mov_b32 v[82:83], v[18:19], v[18:19] op_sel:[0,1]
	global_load_lds_dwordx4 v[2:3], off
	s_waitcnt vmcnt(8)
	s_waitcnt lgkmcnt(0)
	s_barrier
	s_mov_b64 s[8:9], -1
	s_cbranch_vccnz .LBB0_583
	s_mov_b32 s1, 0
	v_add_u32_e32 v6, s1, v132
	ds_read_b128 v[2:5], v6
	ds_read_b128 v[18:21], v6 offset:4096
	v_add_u32_e32 v26, s1, v131
	ds_read_b128 v[22:25], v26
	ds_read_b128 v[134:137], v26 offset:4096
	v_add_u32_e32 v27, s1, v130
	v_add_u32_e32 v26, s1, v128
	s_waitcnt lgkmcnt(0)
	v_mfma_f32_32x32x16_bf16 v[2:17], v[2:5], v[34:37], 0
	ds_read_b128 v[138:141], v27 offset:4096
	v_mfma_f32_32x32x16_bf16 v[2:17], v[22:25], v[38:41], v[2:17]
	ds_read_b128 v[22:25], v27
	s_waitcnt lgkmcnt(0)
	v_mfma_f32_32x32x16_bf16 v[2:17], v[22:25], v[42:45], v[2:17]
	ds_read_b128 v[22:25], v26
	ds_read_b128 v[142:145], v26 offset:4096
	s_waitcnt lgkmcnt(0)
	v_mfma_f32_32x32x16_bf16 v[2:17], v[22:25], v[46:49], v[2:17]
	v_mfma_f32_32x32x16_bf16 v[18:33], v[18:21], v[34:37], 0
	v_mfma_f32_32x32x16_bf16 v[18:33], v[134:137], v[38:41], v[18:33]
	v_mfma_f32_32x32x16_bf16 v[18:33], v[138:141], v[42:45], v[18:33]
	v_mfma_f32_32x32x16_bf16 v[18:33], v[142:145], v[46:49], v[18:33]
	s_nop 7
	s_mov_b32 s1, 0xf149f2ca
	v_max3_f32 v66, v2, v3, v4
	v_max3_f32 v66, v66, v5, v6
	v_max3_f32 v66, v66, v7, v8
	v_max3_f32 v66, v66, v9, v10
	v_max3_f32 v66, v66, v11, v12
	v_max3_f32 v66, v66, v13, v14
	v_max3_f32 v66, v66, v15, v16
	v_max3_f32 v66, v66, v17, v18
	v_max3_f32 v66, v66, v19, v20
	v_max3_f32 v66, v66, v21, v22
	v_max3_f32 v66, v66, v23, v24
	v_max3_f32 v66, v66, v25, v26
	v_max3_f32 v66, v66, v27, v28
	v_max3_f32 v66, v66, v29, v30
	v_max3_f32 v66, v66, v31, v32
	v_max_f32_e32 v66, v66, v33
	v_mul_f32_e32 v66, 0x3e38aa3b, v66
	v_max_f32_e32 v66, s1, v66
	v_mov_b32_e32 v121, v66
	s_nop 1
	v_permlane32_swap_b32 v121, v66
	s_waitcnt lgkmcnt(0)
	v_max3_f32 v121, v110, v66, v121
	v_pk_fma_f32 v[2:3], v[2:3], s[0:1], v[120:121] op_sel:[0,0,1] op_sel_hi:[1,0,1] neg_lo:[0,0,1] neg_hi:[0,0,1]
	v_pk_fma_f32 v[18:19], v[18:19], s[0:1], v[120:121] op_sel:[0,0,1] op_sel_hi:[1,0,1] neg_lo:[0,0,1] neg_hi:[0,0,1]
	v_exp_f32_e32 v133, v2
	v_exp_f32_e32 v165, v18
	v_exp_f32_e32 v66, v3
	v_exp_f32_e32 v142, v19
	v_add_f32_e32 v143, v165, v133
	v_pk_add_f32 v[2:3], v[142:143], v[66:67]
	s_nop 0
	v_pk_add_f32 v[136:137], v[2:3], v[2:3] op_sel_hi:[0,1]
	v_pk_fma_f32 v[4:5], v[4:5], s[0:1], v[120:121] op_sel:[0,0,1] op_sel_hi:[1,0,1] neg_lo:[0,0,1] neg_hi:[0,0,1]
	v_pk_fma_f32 v[20:21], v[20:21], s[0:1], v[120:121] op_sel:[0,0,1] op_sel_hi:[1,0,1] neg_lo:[0,0,1] neg_hi:[0,0,1]
	v_exp_f32_e32 v135, v4
	v_exp_f32_e32 v143, v20
	v_exp_f32_e32 v136, v5
	v_exp_f32_e32 v144, v21
	v_add_f32_e32 v145, v143, v135
	v_pk_add_f32 v[2:3], v[144:145], v[136:137]
	s_nop 0
	v_pk_add_f32 v[138:139], v[2:3], v[2:3] op_sel_hi:[0,1]
	v_pk_fma_f32 v[6:7], v[6:7], s[0:1], v[120:121] op_sel:[0,0,1] op_sel_hi:[1,0,1] neg_lo:[0,0,1] neg_hi:[0,0,1]
	v_pk_fma_f32 v[22:23], v[22:23], s[0:1], v[120:121] op_sel:[0,0,1] op_sel_hi:[1,0,1] neg_lo:[0,0,1] neg_hi:[0,0,1]
	v_exp_f32_e32 v137, v6
	v_exp_f32_e32 v145, v22
	v_exp_f32_e32 v138, v7
	v_exp_f32_e32 v146, v23
	v_add_f32_e32 v147, v145, v137
	v_pk_add_f32 v[2:3], v[146:147], v[138:139]
	s_nop 0
	v_pk_add_f32 v[140:141], v[2:3], v[2:3] op_sel_hi:[0,1]
	v_pk_fma_f32 v[8:9], v[8:9], s[0:1], v[120:121] op_sel:[0,0,1] op_sel_hi:[1,0,1] neg_lo:[0,0,1] neg_hi:[0,0,1]
	v_pk_fma_f32 v[24:25], v[24:25], s[0:1], v[120:121] op_sel:[0,0,1] op_sel_hi:[1,0,1] neg_lo:[0,0,1] neg_hi:[0,0,1]
	v_exp_f32_e32 v139, v8
	v_exp_f32_e32 v147, v24
	v_exp_f32_e32 v140, v9
	v_exp_f32_e32 v148, v25
	v_add_f32_e32 v149, v147, v139
	v_pk_add_f32 v[2:3], v[148:149], v[140:141]
	s_nop 0
	v_pk_add_f32 v[150:151], v[2:3], v[2:3] op_sel_hi:[0,1]
	v_pk_fma_f32 v[10:11], v[10:11], s[0:1], v[120:121] op_sel:[0,0,1] op_sel_hi:[1,0,1] neg_lo:[0,0,1] neg_hi:[0,0,1]
	v_pk_fma_f32 v[26:27], v[26:27], s[0:1], v[120:121] op_sel:[0,0,1] op_sel_hi:[1,0,1] neg_lo:[0,0,1] neg_hi:[0,0,1]
	v_exp_f32_e32 v141, v10
	v_exp_f32_e32 v149, v26
	v_exp_f32_e32 v150, v11
	v_exp_f32_e32 v152, v27
	v_add_f32_e32 v153, v149, v141
	v_pk_add_f32 v[2:3], v[152:153], v[150:151]
	s_nop 0
; #define LAS __attribute__((address_space(3)))
; #define MFMA32(a, b, c) __builtin_amdgcn_mfma_f32_32x32x16_bf16((a), (b), (c), 0, 0, 0)
; __device__ __forceinline__ s16x4 tr_read(LAS unsigned char* p) { return __builtin_bit_cast(s16x4, __builtin_amdgcn_ds_read_tr16_b64_v4i16((LAS v4i16_t*)p)); }
; __device__ __forceinline__ unsigned cvtpk(float lo, float hi) { return pg8::cvt_pk_bf16(lo, hi); }
; template <class ScoreFn>
; __device__ __forceinline__ void attn_step(AttnState& st, const bf16x8 (&qf)[4], LAS unsigned char* kb, LAS unsigned char* vb, int lane, const ScoreFn& sf) {
;     ...
;     for (int i = 0; i < 16; ++i) { s0[i] = __builtin_amdgcn_exp2f(s0[i] - mn); s1[i] = __builtin_amdgcn_exp2f(s1[i] - mn); ps += s0[i] + s1[i]; }
;     st.l = st.l * alpha + ps; st.m = mn;
; #pragma unroll
;     for (int i = 0; i < 16; ++i) { st.o0[i] *= alpha; st.o1[i] *= alpha; }
;     __builtin_amdgcn_sched_barrier(0);
;     v4u pw[4];
;     pw[0].x = cvtpk(s0[0], s0[1]); pw[0].y = cvtpk(s0[2], s0[3]); pw[0].z = cvtpk(s0[4], s0[5]); pw[0].w = cvtpk(s0[6], s0[7]);
;     pw[1].x = cvtpk(s0[8], s0[9]); pw[1].y = cvtpk(s0[10], s0[11]); pw[1].z = cvtpk(s0[12], s0[13]); pw[1].w = cvtpk(s0[14], s0[15]);
;     pw[2].x = cvtpk(s1[0], s1[1]); pw[2].y = cvtpk(s1[2], s1[3]); pw[2].z = cvtpk(s1[4], s1[5]); pw[2].w = cvtpk(s1[6], s1[7]);
;     pw[3].x = cvtpk(s1[8], s1[9]); pw[3].y = cvtpk(s1[10], s1[11]); pw[3].z = cvtpk(s1[12], s1[13]); pw[3].w = cvtpk(s1[14], s1[15]);
;     const int i16 = lane & 15, q = i16 >> 2, p = i16 & 3, dhalf = (lane >> 4) & 1;
;     LAS unsigned char* vrow = vb + (4 * h + q) * KVP + (p & 1) * 8;
;     LAS unsigned char* vp0 = vrow + (((2 * dhalf + (p >> 1)) ^ (4 * h + q)) << 4); LAS unsigned char* vp1 = vrow + (((4 + 2 * dhalf + (p >> 1)) ^ (4 * h + q)) << 4);
; #pragma unroll
;     for (int ks = 0; ks < 4; ++ks) {
;         const s16x4 l0 = tr_read(vp0 + (16 * ks) * KVP), h0 = tr_read(vp0 + (16 * ks + 8) * KVP);
;         const s16x4 l1 = tr_read(vp1 + (16 * ks) * KVP), h1 = tr_read(vp1 + (16 * ks + 8) * KVP);
;         const bf16x8 v0 = (bf16x8){l0[0], l0[1], l0[2], l0[3], h0[0], h0[1], h0[2], h0[3]};
;         const bf16x8 v1 = (bf16x8){l1[0], l1[1], l1[2], l1[3], h1[0], h1[1], h1[2], h1[3]};
;         const bf16x8 pf = __builtin_bit_cast(bf16x8, pw[ks]);
;         st.o0 = MFMA32(v0, pf, st.o0); st.o1 = MFMA32(v1, pf, st.o1);
;     }
	v_pk_add_f32 v[154:155], v[2:3], v[2:3] op_sel_hi:[0,1]
	v_pk_fma_f32 v[12:13], v[12:13], s[0:1], v[120:121] op_sel:[0,0,1] op_sel_hi:[1,0,1] neg_lo:[0,0,1] neg_hi:[0,0,1]
	v_pk_fma_f32 v[28:29], v[28:29], s[0:1], v[120:121] op_sel:[0,0,1] op_sel_hi:[1,0,1] neg_lo:[0,0,1] neg_hi:[0,0,1]
	v_exp_f32_e32 v151, v12
	v_exp_f32_e32 v153, v28
	v_exp_f32_e32 v154, v13
	v_exp_f32_e32 v156, v29
	v_add_f32_e32 v157, v153, v151
	v_pk_add_f32 v[2:3], v[156:157], v[154:155]
	s_nop 0
	v_pk_add_f32 v[158:159], v[2:3], v[2:3] op_sel_hi:[0,1]
	v_pk_fma_f32 v[14:15], v[14:15], s[0:1], v[120:121] op_sel:[0,0,1] op_sel_hi:[1,0,1] neg_lo:[0,0,1] neg_hi:[0,0,1]
	v_pk_fma_f32 v[30:31], v[30:31], s[0:1], v[120:121] op_sel:[0,0,1] op_sel_hi:[1,0,1] neg_lo:[0,0,1] neg_hi:[0,0,1]
	v_exp_f32_e32 v155, v14
	v_exp_f32_e32 v157, v30
	v_exp_f32_e32 v158, v15
	v_exp_f32_e32 v160, v31
	v_add_f32_e32 v161, v157, v155
	v_pk_add_f32 v[2:3], v[160:161], v[158:159]
	s_nop 0
	v_pk_add_f32 v[162:163], v[2:3], v[2:3] op_sel_hi:[0,1]
	v_pk_fma_f32 v[16:17], v[16:17], s[0:1], v[120:121] op_sel:[0,0,1] op_sel_hi:[1,0,1] neg_lo:[0,0,1] neg_hi:[0,0,1]
	v_pk_fma_f32 v[32:33], v[32:33], s[0:1], v[120:121] op_sel:[0,0,1] op_sel_hi:[1,0,1] neg_lo:[0,0,1] neg_hi:[0,0,1]
	v_exp_f32_e32 v159, v16
	v_exp_f32_e32 v161, v32
	v_exp_f32_e32 v162, v17
	v_exp_f32_e32 v166, v33
	v_sub_f32_e32 v2, v110, v121
	v_exp_f32_e32 v18, v2
	v_add_f32_e32 v167, v161, v159
	v_pk_add_f32 v[2:3], v[166:167], v[162:163]
	v_pk_mul_f32 v[16:17], v[80:81], v[18:19] op_sel_hi:[1,0]
	v_add_f32_e32 v129, v2, v3
	v_fmac_f32_e32 v129, v109, v18
	v_pk_mul_f32 v[14:15], v[76:77], v[18:19] op_sel_hi:[1,0]
	v_pk_mul_f32 v[12:13], v[72:73], v[18:19] op_sel_hi:[1,0]
	v_pk_mul_f32 v[10:11], v[68:69], v[18:19] op_sel_hi:[1,0]
	v_pk_mul_f32 v[8:9], v[62:63], v[18:19] op_sel_hi:[1,0]
	v_pk_mul_f32 v[6:7], v[58:59], v[18:19] op_sel_hi:[1,0]
	v_pk_mul_f32 v[4:5], v[54:55], v[18:19] op_sel_hi:[1,0]
	v_pk_mul_f32 v[2:3], v[84:85], v[18:19] op_sel_hi:[1,0]
	v_pk_mul_f32 v[32:33], v[78:79], v[18:19] op_sel_hi:[1,0]
	v_pk_mul_f32 v[30:31], v[74:75], v[18:19] op_sel_hi:[1,0]
	v_pk_mul_f32 v[28:29], v[70:71], v[18:19] op_sel_hi:[1,0]
	v_pk_mul_f32 v[26:27], v[64:65], v[18:19] op_sel_hi:[1,0]
	v_pk_mul_f32 v[24:25], v[60:61], v[18:19] op_sel_hi:[1,0]
	v_pk_mul_f32 v[22:23], v[56:57], v[18:19] op_sel_hi:[1,0]
	v_pk_mul_f32 v[20:21], v[52:53], v[18:19] op_sel_hi:[1,0]
	v_pk_mul_f32 v[18:19], v[82:83], v[18:19] op_sel_hi:[1,0]
	v_cvt_pk_bf16_f32 v135, v135, v136
	v_cvt_pk_bf16_f32 v136, v137, v138
	v_cvt_pk_bf16_f32 v137, v139, v140
	v_cvt_pk_bf16_f32 v138, v141, v150
	v_cvt_pk_bf16_f32 v139, v151, v154
	v_cvt_pk_bf16_f32 v140, v155, v158
	v_cvt_pk_bf16_f32 v143, v143, v144
	v_cvt_pk_bf16_f32 v144, v145, v146
	v_cvt_pk_bf16_f32 v145, v147, v148
	v_cvt_pk_bf16_f32 v146, v149, v152
	v_cvt_pk_bf16_f32 v147, v153, v156
	v_cvt_pk_bf16_f32 v148, v157, v160
	ds_read_b64_tr_b16 v[150:151], v126
	ds_read_b64_tr_b16 v[152:153], v127
	ds_read_b64_tr_b16 v[154:155], v125
	ds_read_b64_tr_b16 v[156:157], v124
	v_cvt_pk_bf16_f32 v134, v133, v66
	v_cvt_pk_bf16_f32 v141, v159, v162
	v_cvt_pk_bf16_f32 v142, v165, v142
	s_waitcnt lgkmcnt(2)
	v_mfma_f32_32x32x16_bf16 v[2:17], v[150:153], v[134:137], v[2:17]
	v_cvt_pk_bf16_f32 v149, v161, v166
	s_mov_b64 s[8:9], 0
	s_waitcnt lgkmcnt(0)
	v_mfma_f32_32x32x16_bf16 v[18:33], v[154:157], v[134:137], v[18:33]
	ds_read_b64_tr_b16 v[134:135], v122
	ds_read_b64_tr_b16 v[136:137], v123
	ds_read_b64_tr_b16 v[150:151], v119
	ds_read_b64_tr_b16 v[152:153], v120
	s_waitcnt lgkmcnt(2)
	v_mfma_f32_32x32x16_bf16 v[2:17], v[134:137], v[138:141], v[2:17]
	s_waitcnt lgkmcnt(0)
	v_mfma_f32_32x32x16_bf16 v[18:33], v[150:153], v[138:141], v[18:33]
	ds_read_b64_tr_b16 v[134:135], v117
	ds_read_b64_tr_b16 v[136:137], v118
	ds_read_b64_tr_b16 v[138:139], v115
	ds_read_b64_tr_b16 v[140:141], v116
	s_waitcnt lgkmcnt(2)
	v_mfma_f32_32x32x16_bf16 v[2:17], v[134:137], v[142:145], v[2:17]
	s_waitcnt lgkmcnt(0)
	v_mfma_f32_32x32x16_bf16 v[18:33], v[138:141], v[142:145], v[18:33]
	ds_read_b64_tr_b16 v[134:135], v113
	ds_read_b64_tr_b16 v[136:137], v114
	ds_read_b64_tr_b16 v[138:139], v111
	ds_read_b64_tr_b16 v[140:141], v112
	s_waitcnt lgkmcnt(2)
	v_mfma_f32_32x32x16_bf16 v[2:17], v[134:137], v[146:149], v[2:17]
	s_waitcnt lgkmcnt(0)
	v_mfma_f32_32x32x16_bf16 v[18:33], v[138:141], v[146:149], v[18:33]
; #define LAS __attribute__((address_space(3)))
; #define MFMA32(a, b, c) __builtin_amdgcn_mfma_f32_32x32x16_bf16((a), (b), (c), 0, 0, 0)
; template <class ScoreFn>
; __device__ __forceinline__ void attn_step(AttnState& st, const bf16x8 (&qf)[4], LAS unsigned char* kb, LAS unsigned char* vb, int lane, const ScoreFn& sf) {
;     ...
;     LAS unsigned char* kp = kb + r * KVP; const int kx = (h ^ (r & 7)) << 4;
; #pragma unroll
;     for (int ds = 0; ds < 4; ++ds) {
;         const bf16x8 k0 = *(const LAS bf16x8*)(kp + (kx ^ (ds << 5))), k1 = *(const LAS bf16x8*)(kp + 32 * KVP + (kx ^ (ds << 5)));
;         s0 = MFMA32(k0, qf[ds], s0); s1 = MFMA32(k1, qf[ds], s1);
;     }
;     float mt = NEG_BIG;
;     __builtin_amdgcn_sched_barrier(0);
; #pragma unroll
;     for (int i = 0; i < 16; ++i) { s0[i] = sf(s0[i], (i & 3) + 8 * (i >> 2), h, r); mt = fmaxf(mt, s0[i]); if ((i & 7) == 7) __builtin_amdgcn_sched_barrier(0); }
; #pragma unroll
;     for (int i = 0; i < 16; ++i) { s1[i] = sf(s1[i], 32 + (i & 3) + 8 * (i >> 2), h, r); mt = fmaxf(mt, s1[i]); if ((i & 7) == 7) __builtin_amdgcn_sched_barrier(0); }
;     mt = fmaxf(mt, __shfl_xor(mt, 32));
.LBB0_583:
	s_andn2_b64 vcc, exec, s[8:9]
	s_cbranch_vccnz .LBB0_585
	s_mov_b32 s1, 0
	v_mov_b32_e32 v66, s14
	s_nop 5
	v_add_u32_e32 v6, s1, v132
	ds_read_b128 v[2:5], v6
	v_add_u32_e32 v10, s1, v131
	v_add_u32_e32 v11, s1, v130
	ds_read_b128 v[130:133], v10 offset:4096
	ds_read_b128 v[6:9], v6 offset:4096
	s_waitcnt lgkmcnt(0)
	v_mfma_f32_32x32x16_bf16 v[18:33], v[2:5], v[34:37], 0
	ds_read_b128 v[2:5], v10
	v_add_u32_e32 v10, s1, v128
	ds_read_b128 v[134:137], v11 offset:4096
	s_waitcnt lgkmcnt(0)
	v_mfma_f32_32x32x16_bf16 v[18:33], v[2:5], v[38:41], v[18:33]
	ds_read_b128 v[2:5], v11
	s_waitcnt lgkmcnt(0)
	v_mfma_f32_32x32x16_bf16 v[18:33], v[2:5], v[42:45], v[18:33]
	ds_read_b128 v[2:5], v10
	ds_read_b128 v[138:141], v10 offset:4096
	s_waitcnt lgkmcnt(0)
	v_mfma_f32_32x32x16_bf16 v[18:33], v[2:5], v[46:49], v[18:33]
	v_mfma_f32_32x32x16_bf16 v[2:17], v[6:9], v[34:37], 0
	v_mfma_f32_32x32x16_bf16 v[2:17], v[130:133], v[38:41], v[2:17]
	v_mfma_f32_32x32x16_bf16 v[2:17], v[134:137], v[42:45], v[2:17]
	v_mfma_f32_32x32x16_bf16 v[2:17], v[138:141], v[46:49], v[2:17]
	v_add_u32_e32 v121, v86, v66
	s_nop 6
	v_mul_f32_e32 v18, 0x3e38aa3b, v18
	v_cmp_gt_u32_e32 vcc, s17, v121
	v_add_u32_e32 v128, 1, v121
	v_mul_f32_e32 v19, 0x3e38aa3b, v19
	v_cndmask_b32_e32 v18, v250, v18, vcc
	v_cmp_gt_u32_e32 vcc, s17, v128
	v_add_u32_e32 v129, 2, v121
	v_mul_f32_e32 v20, 0x3e38aa3b, v20
	v_cndmask_b32_e32 v19, v250, v19, vcc
	v_cmp_gt_u32_e32 vcc, s17, v129
	v_add_u32_e32 v129, 3, v121
	v_mul_f32_e32 v21, 0x3e38aa3b, v21
	v_cndmask_b32_e32 v20, v250, v20, vcc
	v_cmp_gt_u32_e32 vcc, s17, v129
	v_add_u32_e32 v129, 8, v121
	v_mul_f32_e32 v22, 0x3e38aa3b, v22
	v_cndmask_b32_e32 v21, v250, v21, vcc
	v_cmp_gt_u32_e32 vcc, s17, v129
	v_add_u32_e32 v129, 9, v121
	v_mul_f32_e32 v23, 0x3e38aa3b, v23
	v_cndmask_b32_e32 v22, v250, v22, vcc
	v_cmp_gt_u32_e32 vcc, s17, v129
	v_add_u32_e32 v129, 10, v121
	v_mul_f32_e32 v24, 0x3e38aa3b, v24
	v_cndmask_b32_e32 v23, v250, v23, vcc
	v_cmp_gt_u32_e32 vcc, s17, v129
	v_add_u32_e32 v129, 11, v121
	v_mul_f32_e32 v25, 0x3e38aa3b, v25
	v_cndmask_b32_e32 v24, v250, v24, vcc
	v_cmp_gt_u32_e32 vcc, s17, v129
	v_add_u32_e32 v129, 16, v121
	v_mul_f32_e32 v26, 0x3e38aa3b, v26
	v_cndmask_b32_e32 v25, v250, v25, vcc
	v_cmp_gt_u32_e32 vcc, s17, v129
	v_add_u32_e32 v129, 17, v121
	s_mov_b32 s1, 0xf149f2ca
	v_cndmask_b32_e32 v26, v250, v26, vcc
	v_mul_f32_e32 v27, 0x3e38aa3b, v27
	v_cmp_gt_u32_e32 vcc, s17, v129
	v_add_u32_e32 v129, 18, v121
	v_max3_f32 v128, v18, s1, v19
	v_cndmask_b32_e32 v27, v250, v27, vcc
	v_mul_f32_e32 v28, 0x3e38aa3b, v28
	v_cmp_gt_u32_e32 vcc, s17, v129
	v_add_u32_e32 v129, 19, v121
	v_max3_f32 v128, v128, v20, v21
	v_cndmask_b32_e32 v28, v250, v28, vcc
	v_mul_f32_e32 v29, 0x3e38aa3b, v29
	v_cmp_gt_u32_e32 vcc, s17, v129
	v_add_u32_e32 v129, 24, v121
	v_max3_f32 v128, v128, v22, v23
	v_cndmask_b32_e32 v29, v250, v29, vcc
	v_mul_f32_e32 v30, 0x3e38aa3b, v30
	v_cmp_gt_u32_e32 vcc, s17, v129
	v_add_u32_e32 v129, 25, v121
	v_max3_f32 v128, v128, v24, v25
	v_cndmask_b32_e32 v30, v250, v30, vcc
	v_mul_f32_e32 v31, 0x3e38aa3b, v31
	v_cmp_gt_u32_e32 vcc, s17, v129
	v_add_u32_e32 v129, 26, v121
	v_max3_f32 v128, v128, v26, v27
	v_cndmask_b32_e32 v31, v250, v31, vcc
	v_mul_f32_e32 v32, 0x3e38aa3b, v32
	v_cmp_gt_u32_e32 vcc, s17, v129
	v_add_u32_e32 v121, 27, v121
	v_max3_f32 v128, v128, v28, v29
	v_cndmask_b32_e32 v32, v250, v32, vcc
	v_mul_f32_e32 v33, 0x3e38aa3b, v33
	v_cmp_gt_u32_e32 vcc, s17, v121
	v_max3_f32 v128, v128, v30, v31
	v_add_u32_e32 v66, v87, v66
	v_cndmask_b32_e32 v33, v250, v33, vcc
	v_max3_f32 v121, v128, v32, v33
	v_mul_f32_e32 v2, 0x3e38aa3b, v2
	v_cmp_gt_u32_e32 vcc, s17, v66
	v_add_u32_e32 v128, 1, v66
	v_mul_f32_e32 v3, 0x3e38aa3b, v3
	v_cndmask_b32_e32 v2, v250, v2, vcc
	v_cmp_gt_u32_e32 vcc, s17, v128
	v_add_u32_e32 v128, 2, v66
	v_mul_f32_e32 v4, 0x3e38aa3b, v4
	v_cndmask_b32_e32 v3, v250, v3, vcc
	v_cmp_gt_u32_e32 vcc, s17, v128
	v_add_u32_e32 v128, 3, v66
	v_mul_f32_e32 v5, 0x3e38aa3b, v5
	v_cndmask_b32_e32 v4, v250, v4, vcc
	v_cmp_gt_u32_e32 vcc, s17, v128
	v_add_u32_e32 v128, 8, v66
	v_mul_f32_e32 v6, 0x3e38aa3b, v6
	v_cndmask_b32_e32 v5, v250, v5, vcc
	v_cmp_gt_u32_e32 vcc, s17, v128
	v_add_u32_e32 v128, 9, v66
	v_mul_f32_e32 v7, 0x3e38aa3b, v7
	v_cndmask_b32_e32 v6, v250, v6, vcc
	v_cmp_gt_u32_e32 vcc, s17, v128
	v_add_u32_e32 v128, 10, v66
	v_mul_f32_e32 v8, 0x3e38aa3b, v8
	v_cndmask_b32_e32 v7, v250, v7, vcc
	v_cmp_gt_u32_e32 vcc, s17, v128
	v_add_u32_e32 v128, 11, v66
	v_mul_f32_e32 v9, 0x3e38aa3b, v9
	v_cndmask_b32_e32 v8, v250, v8, vcc
	v_cmp_gt_u32_e32 vcc, s17, v128
	v_add_u32_e32 v128, 16, v66
	v_mul_f32_e32 v10, 0x3e38aa3b, v10
	v_cndmask_b32_e32 v9, v250, v9, vcc
	v_cmp_gt_u32_e32 vcc, s17, v128
	v_add_u32_e32 v128, 17, v66
	v_mul_f32_e32 v11, 0x3e38aa3b, v11
	v_cndmask_b32_e32 v10, v250, v10, vcc
	v_cmp_gt_u32_e32 vcc, s17, v128
	v_add_u32_e32 v128, 18, v66
	v_max3_f32 v121, v121, v2, v3
	v_cndmask_b32_e32 v11, v250, v11, vcc
	v_mul_f32_e32 v12, 0x3e38aa3b, v12
	v_cmp_gt_u32_e32 vcc, s17, v128
	v_add_u32_e32 v128, 19, v66
	v_max3_f32 v121, v121, v4, v5
	v_cndmask_b32_e32 v12, v250, v12, vcc
	v_mul_f32_e32 v13, 0x3e38aa3b, v13
	v_cmp_gt_u32_e32 vcc, s17, v128
	v_add_u32_e32 v128, 24, v66
	v_max3_f32 v121, v121, v6, v7
	v_cndmask_b32_e32 v13, v250, v13, vcc
	v_mul_f32_e32 v14, 0x3e38aa3b, v14
	v_cmp_gt_u32_e32 vcc, s17, v128
	v_add_u32_e32 v128, 25, v66
	v_max3_f32 v121, v121, v8, v9
	v_cndmask_b32_e32 v14, v250, v14, vcc
	v_mul_f32_e32 v15, 0x3e38aa3b, v15
	v_cmp_gt_u32_e32 vcc, s17, v128
	v_add_u32_e32 v128, 26, v66
	v_max3_f32 v121, v121, v10, v11
	v_cndmask_b32_e32 v15, v250, v15, vcc
	v_mul_f32_e32 v16, 0x3e38aa3b, v16
	v_cmp_gt_u32_e32 vcc, s17, v128
	v_add_u32_e32 v66, 27, v66
	v_max3_f32 v121, v121, v12, v13
	v_cndmask_b32_e32 v16, v250, v16, vcc
	v_mul_f32_e32 v17, 0x3e38aa3b, v17
	v_cmp_gt_u32_e32 vcc, s17, v66
	v_max3_f32 v121, v121, v14, v15
	s_nop 0
	v_cndmask_b32_e32 v17, v250, v17, vcc
	v_max3_f32 v66, v121, v16, v17
	v_mov_b32_e32 v121, v66
	s_nop 1
	v_permlane32_swap_b32 v121, v66
	s_waitcnt lgkmcnt(0)
; #define LAS __attribute__((address_space(3)))
; #define MFMA32(a, b, c) __builtin_amdgcn_mfma_f32_32x32x16_bf16((a), (b), (c), 0, 0, 0)
; __device__ __forceinline__ unsigned cvtpk(float lo, float hi) { return pg8::cvt_pk_bf16(lo, hi); }
; template <class ScoreFn>
; __device__ __forceinline__ void attn_step(AttnState& st, const bf16x8 (&qf)[4], LAS unsigned char* kb, LAS unsigned char* vb, int lane, const ScoreFn& sf) {
;     ...
;     mt = fmaxf(mt, __shfl_xor(mt, 32));
;     const float mn = fmaxf(st.m, mt), alpha = __builtin_amdgcn_exp2f(st.m - mn);
;     float ps = 0.f;
; #pragma unroll
;     for (int i = 0; i < 16; ++i) { s0[i] = __builtin_amdgcn_exp2f(s0[i] - mn); s1[i] = __builtin_amdgcn_exp2f(s1[i] - mn); ps += s0[i] + s1[i]; }
;     st.l = st.l * alpha + ps; st.m = mn;
; #pragma unroll
;     for (int i = 0; i < 16; ++i) { st.o0[i] *= alpha; st.o1[i] *= alpha; }
;     __builtin_amdgcn_sched_barrier(0);
;     v4u pw[4];
;     pw[0].x = cvtpk(s0[0], s0[1]); pw[0].y = cvtpk(s0[2], s0[3]); pw[0].z = cvtpk(s0[4], s0[5]); pw[0].w = cvtpk(s0[6], s0[7]);
;     pw[1].x = cvtpk(s0[8], s0[9]); pw[1].y = cvtpk(s0[10], s0[11]); pw[1].z = cvtpk(s0[12], s0[13]); pw[1].w = cvtpk(s0[14], s0[15]);
;     pw[2].x = cvtpk(s1[0], s1[1]); pw[2].y = cvtpk(s1[2], s1[3]); pw[2].z = cvtpk(s1[4], s1[5]); pw[2].w = cvtpk(s1[6], s1[7]);
;     pw[3].x = cvtpk(s1[8], s1[9]); pw[3].y = cvtpk(s1[10], s1[11]); pw[3].z = cvtpk(s1[12], s1[13]); pw[3].w = cvtpk(s1[14], s1[15]);
;     const int i16 = lane & 15, q = i16 >> 2, p = i16 & 3, dhalf = (lane >> 4) & 1;
;     LAS unsigned char* vrow = vb + (4 * h + q) * KVP + (p & 1) * 8;
;     LAS unsigned char* vp0 = vrow + (((2 * dhalf + (p >> 1)) ^ (4 * h + q)) << 4); LAS unsigned char* vp1 = vrow + (((4 + 2 * dhalf + (p >> 1)) ^ (4 * h + q)) << 4);
; #pragma unroll
;     for (int ks = 0; ks < 4; ++ks) {
;         const s16x4 l0 = tr_read(vp0 + (16 * ks) * KVP), h0 = tr_read(vp0 + (16 * ks + 8) * KVP);
;         const s16x4 l1 = tr_read(vp1 + (16 * ks) * KVP), h1 = tr_read(vp1 + (16 * ks + 8) * KVP);
;         const bf16x8 v0 = (bf16x8){l0[0], l0[1], l0[2], l0[3], h0[0], h0[1], h0[2], h0[3]};
;         const bf16x8 v1 = (bf16x8){l1[0], l1[1], l1[2], l1[3], h1[0], h1[1], h1[2], h1[3]};
;         const bf16x8 pf = __builtin_bit_cast(bf16x8, pw[ks]);
;         st.o0 = MFMA32(v0, pf, st.o0); st.o1 = MFMA32(v1, pf, st.o1);
;     }
	v_max3_f32 v121, v110, v66, v121
	v_sub_f32_e32 v2, v2, v121
	v_sub_f32_e32 v18, v18, v121
	v_exp_f32_e32 v159, v2
	v_sub_f32_e32 v2, v19, v121
	v_exp_f32_e32 v158, v18
	v_exp_f32_e32 v66, v2
	v_sub_f32_e32 v2, v3, v121
	v_exp_f32_e32 v128, v2
	v_add_f32_e32 v129, v159, v158
	v_pk_add_f32 v[2:3], v[128:129], v[66:67]
	s_nop 0
	v_pk_add_f32 v[130:131], v[2:3], v[2:3] op_sel_hi:[0,1]
	v_sub_f32_e32 v2, v20, v121
	v_exp_f32_e32 v160, v2
	v_sub_f32_e32 v2, v4, v121
	v_exp_f32_e32 v161, v2
	v_sub_f32_e32 v2, v21, v121
	v_exp_f32_e32 v130, v2
	v_sub_f32_e32 v2, v5, v121
	v_exp_f32_e32 v132, v2
	v_add_f32_e32 v133, v161, v160
	v_pk_add_f32 v[2:3], v[132:133], v[130:131]
	s_nop 0
	v_pk_add_f32 v[134:135], v[2:3], v[2:3] op_sel_hi:[0,1]
	v_sub_f32_e32 v2, v22, v121
	v_exp_f32_e32 v131, v2
	v_sub_f32_e32 v2, v6, v121
	v_exp_f32_e32 v133, v2
	v_sub_f32_e32 v2, v23, v121
	v_exp_f32_e32 v134, v2
	v_sub_f32_e32 v2, v7, v121
	v_exp_f32_e32 v136, v2
	v_add_f32_e32 v137, v133, v131
	v_pk_add_f32 v[2:3], v[136:137], v[134:135]
	s_nop 0
	v_pk_add_f32 v[138:139], v[2:3], v[2:3] op_sel_hi:[0,1]
	v_sub_f32_e32 v2, v24, v121
	v_exp_f32_e32 v135, v2
	v_sub_f32_e32 v2, v8, v121
	v_exp_f32_e32 v137, v2
	v_sub_f32_e32 v2, v25, v121
	v_exp_f32_e32 v138, v2
	v_sub_f32_e32 v2, v9, v121
	v_exp_f32_e32 v140, v2
	v_add_f32_e32 v141, v137, v135
	v_pk_add_f32 v[2:3], v[140:141], v[138:139]
	s_nop 0
	v_pk_add_f32 v[142:143], v[2:3], v[2:3] op_sel_hi:[0,1]
	v_sub_f32_e32 v2, v26, v121
	v_exp_f32_e32 v139, v2
	v_sub_f32_e32 v2, v10, v121
	v_exp_f32_e32 v141, v2
	v_sub_f32_e32 v2, v27, v121
	v_exp_f32_e32 v142, v2
	v_sub_f32_e32 v2, v11, v121
	v_exp_f32_e32 v144, v2
	v_add_f32_e32 v145, v141, v139
	v_pk_add_f32 v[2:3], v[144:145], v[142:143]
	s_nop 0
	v_pk_add_f32 v[146:147], v[2:3], v[2:3] op_sel_hi:[0,1]
	v_sub_f32_e32 v2, v28, v121
	v_exp_f32_e32 v143, v2
	v_sub_f32_e32 v2, v12, v121
	v_exp_f32_e32 v145, v2
	v_sub_f32_e32 v2, v29, v121
	v_exp_f32_e32 v146, v2
	v_sub_f32_e32 v2, v13, v121
	v_exp_f32_e32 v148, v2
	v_add_f32_e32 v149, v145, v143
	v_pk_add_f32 v[2:3], v[148:149], v[146:147]
	s_nop 0
	v_pk_add_f32 v[150:151], v[2:3], v[2:3] op_sel_hi:[0,1]
	v_sub_f32_e32 v2, v30, v121
	v_exp_f32_e32 v147, v2
	v_sub_f32_e32 v2, v14, v121
	v_exp_f32_e32 v149, v2
	v_sub_f32_e32 v2, v31, v121
	v_exp_f32_e32 v150, v2
	v_sub_f32_e32 v2, v15, v121
	v_exp_f32_e32 v152, v2
	v_add_f32_e32 v153, v149, v147
	v_pk_add_f32 v[2:3], v[152:153], v[150:151]
	s_nop 0
	v_pk_add_f32 v[154:155], v[2:3], v[2:3] op_sel_hi:[0,1]
	v_sub_f32_e32 v2, v32, v121
	v_exp_f32_e32 v151, v2
	v_sub_f32_e32 v2, v16, v121
	v_exp_f32_e32 v153, v2
	v_sub_f32_e32 v2, v33, v121
	v_exp_f32_e32 v154, v2
	v_sub_f32_e32 v2, v17, v121
	v_exp_f32_e32 v156, v2
	v_sub_f32_e32 v2, v110, v121
	v_exp_f32_e32 v18, v2
	v_add_f32_e32 v157, v153, v151
	v_pk_add_f32 v[2:3], v[156:157], v[154:155]
	v_pk_mul_f32 v[16:17], v[80:81], v[18:19] op_sel_hi:[1,0]
	v_add_f32_e32 v129, v2, v3
	v_fmac_f32_e32 v129, v109, v18
	v_pk_mul_f32 v[14:15], v[76:77], v[18:19] op_sel_hi:[1,0]
	v_pk_mul_f32 v[12:13], v[72:73], v[18:19] op_sel_hi:[1,0]
	v_pk_mul_f32 v[10:11], v[68:69], v[18:19] op_sel_hi:[1,0]
	v_pk_mul_f32 v[8:9], v[62:63], v[18:19] op_sel_hi:[1,0]
	v_pk_mul_f32 v[6:7], v[58:59], v[18:19] op_sel_hi:[1,0]
	v_pk_mul_f32 v[4:5], v[54:55], v[18:19] op_sel_hi:[1,0]
	v_pk_mul_f32 v[2:3], v[84:85], v[18:19] op_sel_hi:[1,0]
	v_pk_mul_f32 v[32:33], v[78:79], v[18:19] op_sel_hi:[1,0]
	v_pk_mul_f32 v[30:31], v[74:75], v[18:19] op_sel_hi:[1,0]
	v_pk_mul_f32 v[28:29], v[70:71], v[18:19] op_sel_hi:[1,0]
	v_pk_mul_f32 v[26:27], v[64:65], v[18:19] op_sel_hi:[1,0]
	v_pk_mul_f32 v[24:25], v[60:61], v[18:19] op_sel_hi:[1,0]
	v_pk_mul_f32 v[22:23], v[56:57], v[18:19] op_sel_hi:[1,0]
	v_pk_mul_f32 v[20:21], v[52:53], v[18:19] op_sel_hi:[1,0]
	v_pk_mul_f32 v[18:19], v[82:83], v[18:19] op_sel_hi:[1,0]
	ds_read_b64_tr_b16 v[72:73], v126
	ds_read_b64_tr_b16 v[74:75], v127
	ds_read_b64_tr_b16 v[76:77], v125
	ds_read_b64_tr_b16 v[78:79], v124
	v_cvt_pk_bf16_f32 v52, v158, v66
	v_cvt_pk_bf16_f32 v53, v160, v130
	v_cvt_pk_bf16_f32 v54, v131, v134
	v_cvt_pk_bf16_f32 v55, v135, v138
	v_cvt_pk_bf16_f32 v56, v139, v142
	v_cvt_pk_bf16_f32 v57, v143, v146
	s_waitcnt lgkmcnt(2)
	v_mfma_f32_32x32x16_bf16 v[2:17], v[72:75], v[52:55], v[2:17]
	v_cvt_pk_bf16_f32 v58, v147, v150
	v_cvt_pk_bf16_f32 v59, v151, v154
	v_cvt_pk_bf16_f32 v60, v159, v128
	v_cvt_pk_bf16_f32 v61, v161, v132
	v_cvt_pk_bf16_f32 v62, v133, v136
	v_cvt_pk_bf16_f32 v63, v137, v140
	v_cvt_pk_bf16_f32 v68, v141, v144
	s_waitcnt lgkmcnt(0)
	v_mfma_f32_32x32x16_bf16 v[18:33], v[76:79], v[52:55], v[18:33]
	ds_read_b64_tr_b16 v[52:53], v122
	ds_read_b64_tr_b16 v[54:55], v123
	ds_read_b64_tr_b16 v[72:73], v119
	ds_read_b64_tr_b16 v[74:75], v120
	v_cvt_pk_bf16_f32 v69, v145, v148
	v_cvt_pk_bf16_f32 v70, v149, v152
	v_cvt_pk_bf16_f32 v71, v153, v156
	s_waitcnt lgkmcnt(2)
	v_mfma_f32_32x32x16_bf16 v[2:17], v[52:55], v[56:59], v[2:17]
	s_waitcnt lgkmcnt(0)
	v_mfma_f32_32x32x16_bf16 v[18:33], v[72:75], v[56:59], v[18:33]
	ds_read_b64_tr_b16 v[52:53], v117
	ds_read_b64_tr_b16 v[54:55], v118
	ds_read_b64_tr_b16 v[56:57], v115
	ds_read_b64_tr_b16 v[58:59], v116
	s_waitcnt lgkmcnt(2)
	v_mfma_f32_32x32x16_bf16 v[2:17], v[52:55], v[60:63], v[2:17]
	s_waitcnt lgkmcnt(0)
	v_mfma_f32_32x32x16_bf16 v[18:33], v[56:59], v[60:63], v[18:33]
	ds_read_b64_tr_b16 v[52:53], v113
	ds_read_b64_tr_b16 v[54:55], v114
	ds_read_b64_tr_b16 v[56:57], v111
	ds_read_b64_tr_b16 v[58:59], v112
	s_waitcnt lgkmcnt(2)
	v_mfma_f32_32x32x16_bf16 v[2:17], v[52:55], v[68:71], v[2:17]
	s_waitcnt lgkmcnt(0)
	v_mfma_f32_32x32x16_bf16 v[18:33], v[56:59], v[68:71], v[18:33]

; #define LAS __attribute__((address_space(3)))
; #define MFMA32(a, b, c) __builtin_amdgcn_mfma_f32_32x32x16_bf16((a), (b), (c), 0, 0, 0)
; #define WG_BAR() do { asm volatile("s_waitcnt lgkmcnt(0)" ::: "memory"); __builtin_amdgcn_s_barrier(); asm volatile("" ::: "memory"); } while (0)
; template <class ScoreFn>
; __device__ __forceinline__ void attn_step(AttnState& st, const bf16x8 (&qf)[4], LAS unsigned char* kb, LAS unsigned char* vb, int lane, const ScoreFn& sf) {
;     ...
;     LAS unsigned char* kp = kb + r * KVP; const int kx = (h ^ (r & 7)) << 4;
; #pragma unroll
;     for (int ds = 0; ds < 4; ++ds) {
;         const bf16x8 k0 = *(const LAS bf16x8*)(kp + (kx ^ (ds << 5))), k1 = *(const LAS bf16x8*)(kp + 32 * KVP + (kx ^ (ds << 5)));
;         s0 = MFMA32(k0, qf[ds], s0); s1 = MFMA32(k1, qf[ds], s1);
;     }
;     float mt = NEG_BIG;
;     __builtin_amdgcn_sched_barrier(0);
; #pragma unroll
;     for (int i = 0; i < 16; ++i) { s0[i] = sf(s0[i], (i & 3) + 8 * (i >> 2), h, r); mt = fmaxf(mt, s0[i]); if ((i & 7) == 7) __builtin_amdgcn_sched_barrier(0); }
; #pragma unroll
;     for (int i = 0; i < 16; ++i) { s1[i] = sf(s1[i], 32 + (i & 3) + 8 * (i >> 2), h, r); mt = fmaxf(mt, s1[i]); if ((i & 7) == 7) __builtin_amdgcn_sched_barrier(0); }
;     mt = fmaxf(mt, __shfl_xor(mt, 32));
;     const float mn = fmaxf(st.m, mt), alpha = __builtin_amdgcn_exp2f(st.m - mn);
;     float ps = 0.f;
; #pragma unroll
;     for (int i = 0; i < 16; ++i) { s0[i] = __builtin_amdgcn_exp2f(s0[i] - mn); s1[i] = __builtin_amdgcn_exp2f(s1[i] - mn); ps += s0[i] + s1[i]; }
; template <bool ISB>
; __device__ __forceinline__ void attn_wg_item(Frame& F, int l, int idx) {
;     ...
;     AttnState st;
; #pragma unroll
;     for (int i = 0; i < 16; ++i) { st.o0[i] = 0.f; st.o1[i] = 0.f; }
;     st.m = NEG_BIG; st.l = 0.f;
; #pragma unroll
;     for (int t = 0; t < ATT_D; ++t) ATT_DMA(t);
;     if (ISB && lat) {
;         const float* bsrc = KIN(I_NBBIAS) + (size_t)(l * 8 + (ix & 7)) * 465;
;         if (tid < 465) tab[64 + tid] = bsrc[tid] * LOG2E; }
;     for (int s = 0; s < NS; ++s) {
;         ATT_DMA(s + ATT_D);
;         asm volatile("s_waitcnt vmcnt(8)" ::: "memory");
;         WG_BAR();
;         LAS unsigned char* cur = ring + (s % ATT_NB) * KV_BUF;
.LBB0_618:
	s_mul_hi_u32 s1, s80, 0xaaaaaaab
	s_lshr_b32 s1, s1, 2
	s_mul_i32 s1, s1, 0x18000
	v_readlane_b32 s2, v253, 14
	s_sub_i32 s74, s2, s1
	v_readlane_b32 s2, v253, 16
	s_sub_i32 s1, s2, s1
	s_mul_hi_u32 s2, s82, 0xaaaaaaab
	s_lshr_b32 s2, s2, 2
	s_add_i32 s75, s82, 4
	s_mul_i32 s2, s2, 0x18000
	s_sub_i32 s2, s81, s2
	s_cmp_lt_i32 s82, s78
	v_add_u32_e32 v139, s2, v96
	v_add_u32_e32 v138, s2, v97
	v_add_u32_e32 v137, s2, v98
	v_add_u32_e32 v136, s2, v99
	v_add3_u32 v134, s2, v100, v101
	v_add3_u32 v133, s2, v102, v101
	v_add3_u32 v129, s2, v103, v101
	v_add3_u32 v128, s2, v104, v101
	v_add3_u32 v125, s2, v105, v101
	v_add3_u32 v124, s2, v106, v101
	v_add3_u32 v121, s2, v107, v101
	v_add3_u32 v120, s2, v108, v101
	v_add3_u32 v118, s2, v110, v101
	v_add3_u32 v119, s2, v111, v101
	v_add3_u32 v122, s2, v112, v101
	v_add3_u32 v123, s2, v113, v101
	v_add3_u32 v126, s2, v114, v101
	v_add3_u32 v127, s2, v115, v101
	v_add3_u32 v132, s2, v116, v101
	v_add3_u32 v135, s2, v117, v101
	s_cselect_b64 s[2:3], -1, 0
	s_and_b64 vcc, s[2:3], exec
	s_cselect_b32 s2, s75, s79
	s_cmp_lt_i32 s2, s78
	s_cselect_b32 s3, 0, s78
	s_cselect_b32 s75, s77, 0x2000
	s_sub_i32 s2, s2, s3
	s_lshl_b32 s2, s2, 6
	s_add_i32 s2, s2, s75
	s_add_i32 s3, s81, s74
	s_add_i32 m0, s3, 0
	v_mad_i64_i32 v[34:35], s[2:3], s2, v249, v[92:93]
	v_lshl_add_u64 v[36:37], v[34:35], 0, s[86:87]
	s_add_i32 s1, s81, s1
	global_load_lds_dwordx4 v[36:37], off
	v_lshl_add_u64 v[34:35], v[34:35], 0, s[96:97]
	s_add_i32 m0, s1, 0
	s_mov_b64 s[74:75], -1
	global_load_lds_dwordx4 v[34:35], off
	s_waitcnt vmcnt(8)
	s_waitcnt lgkmcnt(0)
	s_barrier
	s_cbranch_vccnz .LBB0_620
	s_mov_b32 s1, 0
	v_add_u32_e32 v38, s1, v139
	ds_read_b128 v[34:37], v38
	ds_read_b128 v[50:53], v38 offset:4096
	v_add_u32_e32 v58, s1, v138
	ds_read_b128 v[54:57], v58
	ds_read_b128 v[84:87], v58 offset:4096
	v_add_u32_e32 v59, s1, v137
	v_add_u32_e32 v58, s1, v136
	s_waitcnt lgkmcnt(0)
	v_mfma_f32_32x32x16_bf16 v[34:49], v[34:37], v[68:71], 0
	ds_read_b128 v[88:91], v59 offset:4096
	v_mfma_f32_32x32x16_bf16 v[34:49], v[54:57], v[72:75], v[34:49]
	ds_read_b128 v[54:57], v59
	s_waitcnt lgkmcnt(0)
	v_mfma_f32_32x32x16_bf16 v[34:49], v[54:57], v[76:79], v[34:49]
	ds_read_b128 v[54:57], v58
	ds_read_b128 v[140:143], v58 offset:4096
	s_waitcnt lgkmcnt(0)
	v_mfma_f32_32x32x16_bf16 v[34:49], v[54:57], v[80:83], v[34:49]
	v_mfma_f32_32x32x16_bf16 v[50:65], v[50:53], v[68:71], 0
	v_mfma_f32_32x32x16_bf16 v[50:65], v[84:87], v[72:75], v[50:65]
	v_mfma_f32_32x32x16_bf16 v[50:65], v[88:91], v[76:79], v[50:65]
	v_mfma_f32_32x32x16_bf16 v[50:65], v[140:143], v[80:83], v[50:65]
	s_nop 7
	s_mov_b32 s1, 0xf149f2ca
	v_max3_f32 v66, v34, v35, v36
	v_max3_f32 v66, v66, v37, v38
	v_max3_f32 v66, v66, v39, v40
	v_max3_f32 v66, v66, v41, v42
	v_max3_f32 v66, v66, v43, v44
	v_max3_f32 v66, v66, v45, v46
	v_max3_f32 v66, v66, v47, v48
	v_max3_f32 v66, v66, v49, v50
	v_max3_f32 v66, v66, v51, v52
	v_max3_f32 v66, v66, v53, v54
	v_max3_f32 v66, v66, v55, v56
	v_max3_f32 v66, v66, v57, v58
	v_max3_f32 v66, v66, v59, v60
	v_max3_f32 v66, v66, v61, v62
	v_max3_f32 v66, v66, v63, v64
	v_max_f32_e32 v66, v66, v65
	v_mul_f32_e32 v66, 0x3e38aa3b, v66
	v_max_f32_e32 v66, s1, v66
	v_mov_b32_e32 v84, v66
	s_nop 1
	v_permlane32_swap_b32 v84, v66
	s_waitcnt lgkmcnt(0)
	v_max3_f32 v140, v131, v66, v84
	v_pk_fma_f32 v[34:35], v[34:35], s[0:1], v[140:141] op_sel_hi:[1,0,0] neg_lo:[0,0,1] neg_hi:[0,0,1]
	v_pk_fma_f32 v[50:51], v[50:51], s[0:1], v[140:141] op_sel_hi:[1,0,0] neg_lo:[0,0,1] neg_hi:[0,0,1]
	v_exp_f32_e32 v142, v34
	v_exp_f32_e32 v165, v50
	v_exp_f32_e32 v66, v35
	v_exp_f32_e32 v84, v51
	v_add_f32_e32 v85, v165, v142
	v_pk_add_f32 v[34:35], v[84:85], v[66:67]
	s_nop 0
	v_pk_add_f32 v[86:87], v[34:35], v[34:35] op_sel_hi:[0,1]
	v_pk_fma_f32 v[36:37], v[36:37], s[0:1], v[140:141] op_sel_hi:[1,0,0] neg_lo:[0,0,1] neg_hi:[0,0,1]
	v_pk_fma_f32 v[52:53], v[52:53], s[0:1], v[140:141] op_sel_hi:[1,0,0] neg_lo:[0,0,1] neg_hi:[0,0,1]
	v_exp_f32_e32 v85, v36
	v_exp_f32_e32 v170, v52
	v_exp_f32_e32 v86, v37
	v_exp_f32_e32 v90, v53
	v_add_f32_e32 v91, v170, v85
	v_pk_add_f32 v[34:35], v[90:91], v[86:87]
	s_nop 0
	v_pk_add_f32 v[88:89], v[34:35], v[34:35] op_sel_hi:[0,1]
	v_pk_fma_f32 v[38:39], v[38:39], s[0:1], v[140:141] op_sel_hi:[1,0,0] neg_lo:[0,0,1] neg_hi:[0,0,1]
	v_pk_fma_f32 v[54:55], v[54:55], s[0:1], v[140:141] op_sel_hi:[1,0,0] neg_lo:[0,0,1] neg_hi:[0,0,1]
	v_exp_f32_e32 v87, v38
	v_exp_f32_e32 v91, v54
	v_exp_f32_e32 v88, v39
	v_exp_f32_e32 v150, v55
	v_add_f32_e32 v151, v91, v87
	v_pk_add_f32 v[34:35], v[150:151], v[88:89]
	s_nop 0
	v_pk_add_f32 v[146:147], v[34:35], v[34:35] op_sel_hi:[0,1]
	v_pk_fma_f32 v[40:41], v[40:41], s[0:1], v[140:141] op_sel_hi:[1,0,0] neg_lo:[0,0,1] neg_hi:[0,0,1]
	v_pk_fma_f32 v[56:57], v[56:57], s[0:1], v[140:141] op_sel_hi:[1,0,0] neg_lo:[0,0,1] neg_hi:[0,0,1]
	v_exp_f32_e32 v89, v40
	v_exp_f32_e32 v151, v56
	v_exp_f32_e32 v146, v41
	v_exp_f32_e32 v152, v57
	v_add_f32_e32 v153, v151, v89
	v_pk_add_f32 v[34:35], v[152:153], v[146:147]
	s_nop 0
	v_pk_add_f32 v[148:149], v[34:35], v[34:35] op_sel_hi:[0,1]
	v_pk_fma_f32 v[42:43], v[42:43], s[0:1], v[140:141] op_sel_hi:[1,0,0] neg_lo:[0,0,1] neg_hi:[0,0,1]
	v_pk_fma_f32 v[58:59], v[58:59], s[0:1], v[140:141] op_sel_hi:[1,0,0] neg_lo:[0,0,1] neg_hi:[0,0,1]
	v_exp_f32_e32 v147, v42
	v_exp_f32_e32 v153, v58
	v_exp_f32_e32 v148, v43
	v_exp_f32_e32 v154, v59
	v_add_f32_e32 v155, v153, v147
	v_pk_add_f32 v[34:35], v[154:155], v[148:149]
	s_nop 0
	v_pk_add_f32 v[156:157], v[34:35], v[34:35] op_sel_hi:[0,1]
	v_pk_fma_f32 v[44:45], v[44:45], s[0:1], v[140:141] op_sel_hi:[1,0,0] neg_lo:[0,0,1] neg_hi:[0,0,1]
; template <class ScoreFn>
; __device__ __forceinline__ void attn_step(AttnState& st, const bf16x8 (&qf)[4], LAS unsigned char* kb, LAS unsigned char* vb, int lane, const ScoreFn& sf) {
;     ...
;     for (int i = 0; i < 16; ++i) { s0[i] = __builtin_amdgcn_exp2f(s0[i] - mn); s1[i] = __builtin_amdgcn_exp2f(s1[i] - mn); ps += s0[i] + s1[i]; }
;     st.l = st.l * alpha + ps; st.m = mn;
; #pragma unroll
;     for (int i = 0; i < 16; ++i) { st.o0[i] *= alpha; st.o1[i] *= alpha; }
;     __builtin_amdgcn_sched_barrier(0);
;     v4u pw[4];
;     pw[0].x = cvtpk(s0[0], s0[1]); pw[0].y = cvtpk(s0[2], s0[3]); pw[0].z = cvtpk(s0[4], s0[5]); pw[0].w = cvtpk(s0[6], s0[7]);
;     pw[1].x = cvtpk(s0[8], s0[9]); pw[1].y = cvtpk(s0[10], s0[11]); pw[1].z = cvtpk(s0[12], s0[13]); pw[1].w = cvtpk(s0[14], s0[15]);
;     pw[2].x = cvtpk(s1[0], s1[1]); pw[2].y = cvtpk(s1[2], s1[3]); pw[2].z = cvtpk(s1[4], s1[5]); pw[2].w = cvtpk(s1[6], s1[7]);
;     pw[3].x = cvtpk(s1[8], s1[9]); pw[3].y = cvtpk(s1[10], s1[11]); pw[3].z = cvtpk(s1[12], s1[13]); pw[3].w = cvtpk(s1[14], s1[15]);
;     const int i16 = lane & 15, q = i16 >> 2, p = i16 & 3, dhalf = (lane >> 4) & 1;
;     LAS unsigned char* vrow = vb + (4 * h + q) * KVP + (p & 1) * 8;
;     LAS unsigned char* vp0 = vrow + (((2 * dhalf + (p >> 1)) ^ (4 * h + q)) << 4); LAS unsigned char* vp1 = vrow + (((4 + 2 * dhalf + (p >> 1)) ^ (4 * h + q)) << 4);
; #pragma unroll
;     for (int ks = 0; ks < 4; ++ks) {
;         const s16x4 l0 = tr_read(vp0 + (16 * ks) * KVP), h0 = tr_read(vp0 + (16 * ks + 8) * KVP);
;         const s16x4 l1 = tr_read(vp1 + (16 * ks) * KVP), h1 = tr_read(vp1 + (16 * ks + 8) * KVP);
;         const bf16x8 v0 = (bf16x8){l0[0], l0[1], l0[2], l0[3], h0[0], h0[1], h0[2], h0[3]};
;         const bf16x8 v1 = (bf16x8){l1[0], l1[1], l1[2], l1[3], h1[0], h1[1], h1[2], h1[3]};
;         const bf16x8 pf = __builtin_bit_cast(bf16x8, pw[ks]);
;         st.o0 = MFMA32(v0, pf, st.o0); st.o1 = MFMA32(v1, pf, st.o1);
;     }
; template <bool ISB>
; __device__ __forceinline__ void attn_wg_item(Frame& F, int l, int idx) {
;     ...
;         else { const int gr = r0 + (w >> 1); int kr0 = gr - 4; kr0 = kr0 < 0 ? 0 : (kr0 > 120 ? 120 : kr0); const int kr = kmin + s;
;             if (kr >= kr0 && kr < kr0 + 8) { const int cq = 32 * (w & 1) + (lane & 31), hh = lane >> 5; int cs = cq - 8; cs = cs < 0 ? 0 : (cs > 48 ? 48 : cs);
	v_pk_fma_f32 v[60:61], v[60:61], s[0:1], v[140:141] op_sel_hi:[1,0,0] neg_lo:[0,0,1] neg_hi:[0,0,1]
	v_exp_f32_e32 v149, v44
	v_exp_f32_e32 v155, v60
	v_exp_f32_e32 v156, v45
	v_exp_f32_e32 v158, v61
	v_add_f32_e32 v159, v155, v149
	v_pk_add_f32 v[34:35], v[158:159], v[156:157]
	s_nop 0
	v_pk_add_f32 v[160:161], v[34:35], v[34:35] op_sel_hi:[0,1]
	v_pk_fma_f32 v[46:47], v[46:47], s[0:1], v[140:141] op_sel_hi:[1,0,0] neg_lo:[0,0,1] neg_hi:[0,0,1]
	v_pk_fma_f32 v[62:63], v[62:63], s[0:1], v[140:141] op_sel_hi:[1,0,0] neg_lo:[0,0,1] neg_hi:[0,0,1]
	v_exp_f32_e32 v157, v46
	v_exp_f32_e32 v159, v62
	v_exp_f32_e32 v160, v47
	v_exp_f32_e32 v162, v63
	v_add_f32_e32 v163, v159, v157
	v_pk_add_f32 v[34:35], v[162:163], v[160:161]
	s_nop 0
	v_pk_add_f32 v[166:167], v[34:35], v[34:35] op_sel_hi:[0,1]
	v_pk_fma_f32 v[48:49], v[48:49], s[0:1], v[140:141] op_sel_hi:[1,0,0] neg_lo:[0,0,1] neg_hi:[0,0,1]
	v_pk_fma_f32 v[64:65], v[64:65], s[0:1], v[140:141] op_sel_hi:[1,0,0] neg_lo:[0,0,1] neg_hi:[0,0,1]
	v_exp_f32_e32 v161, v48
	v_exp_f32_e32 v163, v64
	v_exp_f32_e32 v166, v49
	v_exp_f32_e32 v168, v65
	v_sub_f32_e32 v34, v131, v140
	v_exp_f32_e32 v50, v34
	v_add_f32_e32 v169, v163, v161
	v_pk_add_f32 v[34:35], v[168:169], v[166:167]
	v_pk_mul_f32 v[48:49], v[32:33], v[50:51] op_sel_hi:[1,0]
	v_add_f32_e32 v141, v34, v35
	v_fmac_f32_e32 v141, v130, v50
	v_pk_mul_f32 v[46:47], v[30:31], v[50:51] op_sel_hi:[1,0]
	v_pk_mul_f32 v[44:45], v[28:29], v[50:51] op_sel_hi:[1,0]
	v_pk_mul_f32 v[42:43], v[26:27], v[50:51] op_sel_hi:[1,0]
	v_pk_mul_f32 v[40:41], v[24:25], v[50:51] op_sel_hi:[1,0]
	v_pk_mul_f32 v[38:39], v[22:23], v[50:51] op_sel_hi:[1,0]
	v_pk_mul_f32 v[36:37], v[20:21], v[50:51] op_sel_hi:[1,0]
	v_pk_mul_f32 v[34:35], v[18:19], v[50:51] op_sel_hi:[1,0]
	v_pk_mul_f32 v[64:65], v[16:17], v[50:51] op_sel_hi:[1,0]
	v_pk_mul_f32 v[62:63], v[14:15], v[50:51] op_sel_hi:[1,0]
	v_pk_mul_f32 v[60:61], v[12:13], v[50:51] op_sel_hi:[1,0]
	v_pk_mul_f32 v[58:59], v[10:11], v[50:51] op_sel_hi:[1,0]
	v_pk_mul_f32 v[56:57], v[8:9], v[50:51] op_sel_hi:[1,0]
	v_pk_mul_f32 v[54:55], v[6:7], v[50:51] op_sel_hi:[1,0]
	v_pk_mul_f32 v[52:53], v[4:5], v[50:51] op_sel_hi:[1,0]
	v_pk_mul_f32 v[50:51], v[2:3], v[50:51] op_sel_hi:[1,0]
	v_cvt_pk_bf16_f32 v142, v142, v66
	v_cvt_pk_bf16_f32 v144, v87, v88
	v_cvt_pk_bf16_f32 v145, v89, v146
	v_cvt_pk_bf16_f32 v88, v165, v84
	v_cvt_pk_bf16_f32 v89, v170, v90
	v_cvt_pk_bf16_f32 v90, v91, v150
	v_cvt_pk_bf16_f32 v91, v151, v152
	v_cvt_pk_bf16_f32 v84, v153, v154
	ds_read_b64_tr_b16 v[150:151], v134
	v_cvt_pk_bf16_f32 v143, v85, v86
	v_cvt_pk_bf16_f32 v85, v155, v158
	ds_read_b64_tr_b16 v[152:153], v133
	ds_read_b64_tr_b16 v[154:155], v135
	v_cvt_pk_bf16_f32 v146, v147, v148
	v_cvt_pk_bf16_f32 v147, v149, v156
	v_cvt_pk_bf16_f32 v148, v157, v160
	ds_read_b64_tr_b16 v[156:157], v132
	s_waitcnt lgkmcnt(2)
	v_mfma_f32_32x32x16_bf16 v[34:49], v[150:153], v[142:145], v[34:49]
	v_cvt_pk_bf16_f32 v149, v161, v166
	v_cvt_pk_bf16_f32 v86, v159, v162
	v_cvt_pk_bf16_f32 v87, v163, v168
	s_mov_b64 s[74:75], 0
	s_waitcnt lgkmcnt(0)
	v_mfma_f32_32x32x16_bf16 v[50:65], v[154:157], v[142:145], v[50:65]
	ds_read_b64_tr_b16 v[142:143], v129
	ds_read_b64_tr_b16 v[144:145], v128
	ds_read_b64_tr_b16 v[150:151], v127
	ds_read_b64_tr_b16 v[152:153], v126
	s_waitcnt lgkmcnt(2)
	v_mfma_f32_32x32x16_bf16 v[34:49], v[142:145], v[146:149], v[34:49]
	ds_read_b64_tr_b16 v[142:143], v125
	ds_read_b64_tr_b16 v[144:145], v124
	s_waitcnt lgkmcnt(2)
	v_mfma_f32_32x32x16_bf16 v[50:65], v[150:153], v[146:149], v[50:65]
	ds_read_b64_tr_b16 v[146:147], v123
	ds_read_b64_tr_b16 v[148:149], v122
	s_waitcnt lgkmcnt(2)
	v_mfma_f32_32x32x16_bf16 v[34:49], v[142:145], v[88:91], v[34:49]
	s_waitcnt lgkmcnt(0)
	v_mfma_f32_32x32x16_bf16 v[50:65], v[146:149], v[88:91], v[50:65]
	ds_read_b64_tr_b16 v[88:89], v121
	ds_read_b64_tr_b16 v[90:91], v120
	ds_read_b64_tr_b16 v[142:143], v119
	ds_read_b64_tr_b16 v[144:145], v118
	s_waitcnt lgkmcnt(2)
	v_mfma_f32_32x32x16_bf16 v[34:49], v[88:91], v[84:87], v[34:49]
	s_waitcnt lgkmcnt(0)
	v_mfma_f32_32x32x16_bf16 v[50:65], v[142:145], v[84:87], v[50:65]
.LBB0_620:
	s_andn2_b64 vcc, exec, s[74:75]
	s_cbranch_vccnz .LBB0_624
	s_add_i32 s1, s76, s82
	v_cmp_ge_u32_e32 vcc, s1, v94
	v_cmp_lt_u32_e64 s[74:75], s1, v95
	s_and_b64 s[2:3], vcc, s[74:75]
	s_andn2_b64 vcc, exec, s[2:3]
	s_cbranch_vccnz .LBB0_623
; #define LAS __attribute__((address_space(3)))
; #define MFMA32(a, b, c) __builtin_amdgcn_mfma_f32_32x32x16_bf16((a), (b), (c), 0, 0, 0)
;     __device__ __forceinline__ float operator()(float s, int kc, int h, int qr) const { const int d = dk + kc + 4 * h - qr; return (d >= -128 && d <= 128) ? s * (ATT_SCALE * LOG2E) : NEG_BIG; }
; template <class ScoreFn>
; __device__ __forceinline__ void attn_step(AttnState& st, const bf16x8 (&qf)[4], LAS unsigned char* kb, LAS unsigned char* vb, int lane, const ScoreFn& sf) {
;     ...
;     LAS unsigned char* kp = kb + r * KVP; const int kx = (h ^ (r & 7)) << 4;
; #pragma unroll
;     for (int ds = 0; ds < 4; ++ds) {
;         const bf16x8 k0 = *(const LAS bf16x8*)(kp + (kx ^ (ds << 5))), k1 = *(const LAS bf16x8*)(kp + 32 * KVP + (kx ^ (ds << 5)));
;         s0 = MFMA32(k0, qf[ds], s0); s1 = MFMA32(k1, qf[ds], s1);
;     }
;     float mt = NEG_BIG;
;     __builtin_amdgcn_sched_barrier(0);
; #pragma unroll
;     for (int i = 0; i < 16; ++i) { s0[i] = sf(s0[i], (i & 3) + 8 * (i >> 2), h, r); mt = fmaxf(mt, s0[i]); if ((i & 7) == 7) __builtin_amdgcn_sched_barrier(0); }
; #pragma unroll
;     for (int i = 0; i < 16; ++i) { s1[i] = sf(s1[i], 32 + (i & 3) + 8 * (i >> 2), h, r); mt = fmaxf(mt, s1[i]); if ((i & 7) == 7) __builtin_amdgcn_sched_barrier(0); }
;     mt = fmaxf(mt, __shfl_xor(mt, 32));
;     __device__ __forceinline__ float operator()(float s, int kc, int, int) const {
;         const float b = *(const LAS float*)(tbs + 4 * kc);
;         return (kc >= lo4 && kc < lo4 + 16) ? fmaf(s, ATT_SCALE * LOG2E, b) : NEG_BIG;
;     }
	s_mov_b32 s1, 0
	s_nop 0
	v_add_u32_e32 v38, s1, v139
	ds_read_b128 v[34:37], v38
	ds_read_b128 v[50:53], v38 offset:4096
	v_add_u32_e32 v58, s1, v138
	ds_read_b128 v[54:57], v58
	ds_read_b128 v[84:87], v58 offset:4096
	v_add_u32_e32 v59, s1, v137
	v_add_u32_e32 v58, s1, v136
	v_add_u32_e32 v66, 0, v109
	s_waitcnt lgkmcnt(0)
	v_mfma_f32_32x32x16_bf16 v[34:49], v[34:37], v[68:71], 0
	ds_read_b128 v[88:91], v59 offset:4096
	ds_read_b128 v[136:139], v58 offset:4096
	v_mfma_f32_32x32x16_bf16 v[34:49], v[54:57], v[72:75], v[34:49]
	ds_read_b128 v[54:57], v59
	v_add_u32_e32 v59, 0x184a0, v66
	s_waitcnt lgkmcnt(0)
	v_mfma_f32_32x32x16_bf16 v[34:49], v[54:57], v[76:79], v[34:49]
	ds_read_b128 v[54:57], v58
	s_waitcnt lgkmcnt(0)
	v_mfma_f32_32x32x16_bf16 v[34:49], v[54:57], v[80:83], v[34:49]
	v_add_u32_e32 v54, 0x184a8, v66
	v_add_u32_e32 v55, 0x184c0, v66
	v_add_u32_e32 v56, 0x184c8, v66
	ds_read2_b32 v[140:141], v59 offset1:1
	ds_read2_b32 v[142:143], v54 offset1:1
	ds_read2_b32 v[144:145], v55 offset1:1
	ds_read2_b32 v[146:147], v56 offset1:1
	v_add_u32_e32 v54, 0x184e0, v66
	v_add_u32_e32 v55, 0x184e8, v66
	v_add_u32_e32 v56, 0x18500, v66
	v_add_u32_e32 v57, 0x18508, v66
	ds_read2_b32 v[148:149], v54 offset1:1
	ds_read2_b32 v[150:151], v55 offset1:1
	ds_read2_b32 v[152:153], v56 offset1:1
	ds_read2_b32 v[154:155], v57 offset1:1
	v_mfma_f32_32x32x16_bf16 v[50:65], v[50:53], v[68:71], 0
	v_mfma_f32_32x32x16_bf16 v[50:65], v[84:87], v[72:75], v[50:65]
	v_add_u32_e32 v84, 0x18520, v66
	v_add_u32_e32 v86, 0x18528, v66
	v_mfma_f32_32x32x16_bf16 v[50:65], v[88:91], v[76:79], v[50:65]
	v_add_u32_e32 v88, 0x18540, v66
	v_add_u32_e32 v90, 0x18548, v66
	ds_read2_b32 v[84:85], v84 offset1:1
	ds_read2_b32 v[86:87], v86 offset1:1
	ds_read2_b32 v[88:89], v88 offset1:1
	ds_read2_b32 v[90:91], v90 offset1:1
	v_mfma_f32_32x32x16_bf16 v[50:65], v[136:139], v[80:83], v[50:65]
	v_add_u32_e32 v136, 0x18560, v66
	v_add_u32_e32 v138, 0x18568, v66
	v_add_u32_e32 v156, 0x18580, v66
	v_add_u32_e32 v66, 0x18588, v66
	ds_read2_b32 v[136:137], v136 offset1:1
	ds_read2_b32 v[138:139], v138 offset1:1
	ds_read2_b32 v[156:157], v156 offset1:1
	ds_read2_b32 v[158:159], v66 offset1:1
	s_waitcnt lgkmcnt(0)
	v_fmamk_f32 v34, v34, 0x3e38aa3b, v140
	v_fmac_f32_e32 v141, 0x3e38aa3b, v35
	v_cndmask_b32_e64 v34, v250, v34, s[6:7]
	v_cndmask_b32_e64 v35, v250, v141, s[8:9]
	s_mov_b32 s1, 0xf149f2ca
	v_fmamk_f32 v36, v36, 0x3e38aa3b, v142
	v_fmac_f32_e32 v143, 0x3e38aa3b, v37
	v_max3_f32 v66, v34, s1, v35
	v_cndmask_b32_e64 v140, v250, v36, s[10:11]
	v_cndmask_b32_e64 v141, v250, v143, s[12:13]
	v_fmamk_f32 v37, v38, 0x3e38aa3b, v144
	v_fmac_f32_e32 v145, 0x3e38aa3b, v39
	v_max3_f32 v36, v66, v140, v141
	v_cndmask_b32_e64 v142, v250, v37, s[14:15]
	v_cndmask_b32_e64 v143, v250, v145, s[16:17]
	v_fmamk_f32 v37, v40, 0x3e38aa3b, v146
	v_fmac_f32_e32 v147, 0x3e38aa3b, v41
	v_max3_f32 v36, v36, v142, v143
	v_cndmask_b32_e64 v144, v250, v37, s[18:19]
	v_cndmask_b32_e64 v145, v250, v147, s[20:21]
	v_fmamk_f32 v37, v42, 0x3e38aa3b, v148
	v_fmac_f32_e32 v149, 0x3e38aa3b, v43
	v_max3_f32 v36, v36, v144, v145
	v_cndmask_b32_e64 v146, v250, v37, s[22:23]
	v_cndmask_b32_e64 v43, v250, v149, s[24:25]
	v_fmamk_f32 v37, v44, 0x3e38aa3b, v150
	v_fmac_f32_e32 v151, 0x3e38aa3b, v45
	v_max3_f32 v36, v36, v146, v43
	v_cndmask_b32_e64 v147, v250, v37, s[26:27]
	v_cndmask_b32_e64 v148, v250, v151, s[28:29]
	v_fmamk_f32 v37, v46, 0x3e38aa3b, v152
	v_fmac_f32_e32 v153, 0x3e38aa3b, v47
	v_max3_f32 v36, v36, v147, v148
	v_cndmask_b32_e64 v46, v250, v37, s[30:31]
	v_cndmask_b32_e64 v47, v250, v153, s[34:35]
	v_fmamk_f32 v37, v48, 0x3e38aa3b, v154
	v_fmac_f32_e32 v155, 0x3e38aa3b, v49
	v_max3_f32 v36, v36, v46, v47
	v_cndmask_b32_e64 v149, v250, v37, s[36:37]
	v_cndmask_b32_e64 v150, v250, v155, s[38:39]
	v_fmamk_f32 v37, v50, 0x3e38aa3b, v84
	v_fmac_f32_e32 v85, 0x3e38aa3b, v51
	v_max3_f32 v36, v36, v149, v150
	v_cndmask_b32_e64 v37, v250, v37, s[40:41]
	v_cndmask_b32_e64 v38, v250, v85, s[42:43]
	v_fmamk_f32 v39, v52, 0x3e38aa3b, v86
	v_fmac_f32_e32 v87, 0x3e38aa3b, v53
	v_max3_f32 v36, v36, v37, v38
	v_cndmask_b32_e64 v39, v250, v39, s[44:45]
	v_cndmask_b32_e64 v40, v250, v87, s[46:47]
	v_fmamk_f32 v41, v54, 0x3e38aa3b, v88
	v_fmac_f32_e32 v89, 0x3e38aa3b, v55
	v_max3_f32 v36, v36, v39, v40
	v_cndmask_b32_e64 v44, v250, v41, s[48:49]
	v_cndmask_b32_e64 v45, v250, v89, s[50:51]
	v_fmamk_f32 v41, v56, 0x3e38aa3b, v90
	v_fmac_f32_e32 v91, 0x3e38aa3b, v57
	v_max3_f32 v36, v36, v44, v45
	v_cndmask_b32_e64 v50, v250, v41, s[52:53]
	v_cndmask_b32_e64 v51, v250, v91, s[54:55]
	v_fmamk_f32 v41, v58, 0x3e38aa3b, v136
	v_fmac_f32_e32 v137, 0x3e38aa3b, v59
	v_max3_f32 v36, v36, v50, v51
	v_cndmask_b32_e64 v56, v250, v41, s[56:57]
	v_cndmask_b32_e64 v57, v250, v137, s[58:59]
	v_fmamk_f32 v41, v60, 0x3e38aa3b, v138
	v_fmac_f32_e32 v139, 0x3e38aa3b, v61
	v_max3_f32 v36, v36, v56, v57
	v_cndmask_b32_e64 v60, v250, v41, s[60:61]
	v_cndmask_b32_e64 v61, v250, v139, s[62:63]
	v_fmamk_f32 v41, v62, 0x3e38aa3b, v156
	v_fmac_f32_e32 v157, 0x3e38aa3b, v63
	v_max3_f32 v36, v36, v60, v61
	v_cndmask_b32_e64 v84, v250, v41, s[64:65]
	v_cndmask_b32_e64 v85, v250, v157, s[66:67]
	v_fmamk_f32 v41, v64, 0x3e38aa3b, v158
	v_fmac_f32_e32 v159, 0x3e38aa3b, v65
	v_max3_f32 v36, v36, v84, v85
	v_cndmask_b32_e64 v86, v250, v41, s[68:69]
	v_cndmask_b32_e64 v87, v250, v159, s[70:71]
	v_max3_f32 v36, v36, v86, v87
	v_mov_b32_e32 v41, v36
	s_nop 1
	v_permlane32_swap_b32 v41, v36
	s_waitcnt lgkmcnt(0)
; #define LAS __attribute__((address_space(3)))
; #define MFMA32(a, b, c) __builtin_amdgcn_mfma_f32_32x32x16_bf16((a), (b), (c), 0, 0, 0)
; __device__ __forceinline__ unsigned cvtpk(float lo, float hi) { return pg8::cvt_pk_bf16(lo, hi); }
; template <class ScoreFn>
; __device__ __forceinline__ void attn_step(AttnState& st, const bf16x8 (&qf)[4], LAS unsigned char* kb, LAS unsigned char* vb, int lane, const ScoreFn& sf) {
;     ...
;     mt = fmaxf(mt, __shfl_xor(mt, 32));
;     const float mn = fmaxf(st.m, mt), alpha = __builtin_amdgcn_exp2f(st.m - mn);
;     float ps = 0.f;
; #pragma unroll
;     for (int i = 0; i < 16; ++i) { s0[i] = __builtin_amdgcn_exp2f(s0[i] - mn); s1[i] = __builtin_amdgcn_exp2f(s1[i] - mn); ps += s0[i] + s1[i]; }
;     st.l = st.l * alpha + ps; st.m = mn;
; #pragma unroll
;     for (int i = 0; i < 16; ++i) { st.o0[i] *= alpha; st.o1[i] *= alpha; }
;     __builtin_amdgcn_sched_barrier(0);
;     v4u pw[4];
;     pw[0].x = cvtpk(s0[0], s0[1]); pw[0].y = cvtpk(s0[2], s0[3]); pw[0].z = cvtpk(s0[4], s0[5]); pw[0].w = cvtpk(s0[6], s0[7]);
;     pw[1].x = cvtpk(s0[8], s0[9]); pw[1].y = cvtpk(s0[10], s0[11]); pw[1].z = cvtpk(s0[12], s0[13]); pw[1].w = cvtpk(s0[14], s0[15]);
;     pw[2].x = cvtpk(s1[0], s1[1]); pw[2].y = cvtpk(s1[2], s1[3]); pw[2].z = cvtpk(s1[4], s1[5]); pw[2].w = cvtpk(s1[6], s1[7]);
;     pw[3].x = cvtpk(s1[8], s1[9]); pw[3].y = cvtpk(s1[10], s1[11]); pw[3].z = cvtpk(s1[12], s1[13]); pw[3].w = cvtpk(s1[14], s1[15]);
;     const int i16 = lane & 15, q = i16 >> 2, p = i16 & 3, dhalf = (lane >> 4) & 1;
;     LAS unsigned char* vrow = vb + (4 * h + q) * KVP + (p & 1) * 8;
;     LAS unsigned char* vp0 = vrow + (((2 * dhalf + (p >> 1)) ^ (4 * h + q)) << 4); LAS unsigned char* vp1 = vrow + (((4 + 2 * dhalf + (p >> 1)) ^ (4 * h + q)) << 4);
; #pragma unroll
;     for (int ks = 0; ks < 4; ++ks) {
;         const s16x4 l0 = tr_read(vp0 + (16 * ks) * KVP), h0 = tr_read(vp0 + (16 * ks + 8) * KVP);
;         const s16x4 l1 = tr_read(vp1 + (16 * ks) * KVP), h1 = tr_read(vp1 + (16 * ks + 8) * KVP);
;         const bf16x8 v0 = (bf16x8){l0[0], l0[1], l0[2], l0[3], h0[0], h0[1], h0[2], h0[3]};
;         const bf16x8 v1 = (bf16x8){l1[0], l1[1], l1[2], l1[3], h1[0], h1[1], h1[2], h1[3]};
;         const bf16x8 pf = __builtin_bit_cast(bf16x8, pw[ks]);
;         st.o0 = MFMA32(v0, pf, st.o0); st.o1 = MFMA32(v1, pf, st.o1);
;     }
	v_max3_f32 v42, v131, v36, v41
	v_sub_f32_e32 v34, v34, v42
	v_exp_f32_e32 v88, v34
	v_sub_f32_e32 v34, v37, v42
	v_exp_f32_e32 v89, v34
	v_sub_f32_e32 v34, v35, v42
	v_exp_f32_e32 v66, v34
	v_sub_f32_e32 v34, v38, v42
	v_exp_f32_e32 v34, v34
	v_add_f32_e32 v35, v89, v88
	v_sub_f32_e32 v38, v40, v42
	v_exp_f32_e32 v40, v38
	v_pk_add_f32 v[36:37], v[34:35], v[66:67]
	v_sub_f32_e32 v35, v140, v42
	v_pk_add_f32 v[36:37], v[36:37], v[36:37] op_sel_hi:[0,1]
	v_sub_f32_e32 v36, v39, v42
	v_exp_f32_e32 v35, v35
	v_exp_f32_e32 v90, v36
	v_sub_f32_e32 v36, v141, v42
	v_exp_f32_e32 v36, v36
	v_sub_f32_e32 v43, v43, v42
	v_add_f32_e32 v41, v90, v35
	v_pk_add_f32 v[38:39], v[40:41], v[36:37]
	s_nop 0
	v_pk_add_f32 v[38:39], v[38:39], v[38:39] op_sel_hi:[0,1]
	v_sub_f32_e32 v37, v142, v42
	v_sub_f32_e32 v38, v44, v42
	v_exp_f32_e32 v37, v37
	v_exp_f32_e32 v41, v38
	v_sub_f32_e32 v38, v143, v42
	v_sub_f32_e32 v44, v45, v42
	v_exp_f32_e32 v38, v38
	v_exp_f32_e32 v52, v44
	v_add_f32_e32 v53, v41, v37
	v_pk_add_f32 v[44:45], v[52:53], v[38:39]
	s_nop 0
	v_pk_add_f32 v[48:49], v[44:45], v[44:45] op_sel_hi:[0,1]
	v_sub_f32_e32 v44, v50, v42
	v_sub_f32_e32 v39, v144, v42
	v_exp_f32_e32 v53, v44
	v_sub_f32_e32 v44, v145, v42
	v_exp_f32_e32 v39, v39
	v_exp_f32_e32 v48, v44
	v_sub_f32_e32 v44, v51, v42
	v_exp_f32_e32 v54, v44
	v_add_f32_e32 v55, v53, v39
	v_pk_add_f32 v[44:45], v[54:55], v[48:49]
	s_nop 0
	v_pk_add_f32 v[50:51], v[44:45], v[44:45] op_sel_hi:[0,1]
	v_sub_f32_e32 v44, v146, v42
	v_exp_f32_e32 v49, v44
	v_sub_f32_e32 v44, v56, v42
	v_exp_f32_e32 v55, v44
	v_exp_f32_e32 v50, v43
	v_sub_f32_e32 v43, v57, v42
	v_exp_f32_e32 v56, v43
	v_add_f32_e32 v57, v55, v49
	v_sub_f32_e32 v43, v147, v42
	v_exp_f32_e32 v43, v43
	v_pk_add_f32 v[44:45], v[56:57], v[50:51]
	s_nop 0
	v_pk_add_f32 v[58:59], v[44:45], v[44:45] op_sel_hi:[0,1]
	v_sub_f32_e32 v44, v60, v42
	v_exp_f32_e32 v57, v44
	v_sub_f32_e32 v44, v148, v42
	v_exp_f32_e32 v58, v44
	v_sub_f32_e32 v44, v61, v42
	v_exp_f32_e32 v60, v44
	v_add_f32_e32 v61, v57, v43
	v_pk_add_f32 v[44:45], v[60:61], v[58:59]
	s_nop 0
	v_pk_add_f32 v[62:63], v[44:45], v[44:45] op_sel_hi:[0,1]
	v_sub_f32_e32 v44, v46, v42
	v_exp_f32_e32 v51, v44
	v_sub_f32_e32 v44, v84, v42
	v_exp_f32_e32 v59, v44
	v_sub_f32_e32 v44, v47, v42
	v_exp_f32_e32 v62, v44
	v_sub_f32_e32 v44, v85, v42
	v_exp_f32_e32 v64, v44
	v_add_f32_e32 v65, v59, v51
	v_pk_add_f32 v[44:45], v[64:65], v[62:63]
	s_nop 0
	v_pk_add_f32 v[84:85], v[44:45], v[44:45] op_sel_hi:[0,1]
	v_sub_f32_e32 v44, v149, v42
	v_exp_f32_e32 v61, v44
	v_sub_f32_e32 v44, v86, v42
	v_exp_f32_e32 v63, v44
	v_sub_f32_e32 v44, v150, v42
	v_exp_f32_e32 v84, v44
	v_sub_f32_e32 v44, v87, v42
	v_exp_f32_e32 v86, v44
	v_sub_f32_e32 v44, v131, v42
	v_exp_f32_e32 v44, v44
	v_add_f32_e32 v87, v63, v61
	v_pk_add_f32 v[46:47], v[86:87], v[84:85]
	v_pk_mul_f32 v[32:33], v[32:33], v[44:45] op_sel_hi:[1,0]
	v_add_f32_e32 v65, v46, v47
	v_pk_mul_f32 v[30:31], v[30:31], v[44:45] op_sel_hi:[1,0]
	v_pk_mul_f32 v[28:29], v[28:29], v[44:45] op_sel_hi:[1,0]
	v_pk_mul_f32 v[26:27], v[26:27], v[44:45] op_sel_hi:[1,0]
	v_pk_mul_f32 v[24:25], v[24:25], v[44:45] op_sel_hi:[1,0]
	v_pk_mul_f32 v[22:23], v[22:23], v[44:45] op_sel_hi:[1,0]
	v_pk_mul_f32 v[20:21], v[20:21], v[44:45] op_sel_hi:[1,0]
	v_pk_mul_f32 v[18:19], v[18:19], v[44:45] op_sel_hi:[1,0]
	v_pk_mul_f32 v[16:17], v[16:17], v[44:45] op_sel_hi:[1,0]
	v_pk_mul_f32 v[14:15], v[14:15], v[44:45] op_sel_hi:[1,0]
	v_pk_mul_f32 v[12:13], v[12:13], v[44:45] op_sel_hi:[1,0]
	v_pk_mul_f32 v[10:11], v[10:11], v[44:45] op_sel_hi:[1,0]
	v_pk_mul_f32 v[8:9], v[8:9], v[44:45] op_sel_hi:[1,0]
	v_pk_mul_f32 v[6:7], v[6:7], v[44:45] op_sel_hi:[1,0]
	v_pk_mul_f32 v[4:5], v[4:5], v[44:45] op_sel_hi:[1,0]
	v_pk_mul_f32 v[2:3], v[2:3], v[44:45] op_sel_hi:[1,0]
	v_fmac_f32_e32 v65, v130, v44
	v_cvt_pk_bf16_f32 v47, v39, v48
	v_cvt_pk_bf16_f32 v48, v49, v50
	v_cvt_pk_bf16_f32 v49, v43, v58
	v_cvt_pk_bf16_f32 v46, v37, v38
	v_cvt_pk_bf16_f32 v38, v89, v34
	v_cvt_pk_bf16_f32 v39, v90, v40
	v_cvt_pk_bf16_f32 v40, v41, v52
	v_cvt_pk_bf16_f32 v41, v53, v54
	v_cvt_pk_bf16_f32 v34, v55, v56
	ds_read_b64_tr_b16 v[52:53], v134
	v_cvt_pk_bf16_f32 v45, v35, v36
	v_cvt_pk_bf16_f32 v35, v57, v60
	ds_read_b64_tr_b16 v[54:55], v133
	ds_read_b64_tr_b16 v[56:57], v135
	v_cvt_pk_bf16_f32 v36, v59, v64
	ds_read_b64_tr_b16 v[58:59], v132
	v_cvt_pk_bf16_f32 v44, v88, v66
	v_cvt_pk_bf16_f32 v50, v51, v62
	s_waitcnt lgkmcnt(2)
	v_mfma_f32_32x32x16_bf16 v[18:33], v[52:55], v[44:47], v[18:33]
	v_cvt_pk_bf16_f32 v51, v61, v84
	v_cvt_pk_bf16_f32 v37, v63, v86
	v_mov_b32_e32 v130, v65
	v_mov_b32_e32 v131, v42
	s_waitcnt lgkmcnt(0)
	v_mfma_f32_32x32x16_bf16 v[2:17], v[56:59], v[44:47], v[2:17]
	ds_read_b64_tr_b16 v[44:45], v129
	ds_read_b64_tr_b16 v[46:47], v128
	ds_read_b64_tr_b16 v[52:53], v127
	ds_read_b64_tr_b16 v[54:55], v126
	s_waitcnt lgkmcnt(2)
	v_mfma_f32_32x32x16_bf16 v[18:33], v[44:47], v[48:51], v[18:33]
	ds_read_b64_tr_b16 v[44:45], v125
	ds_read_b64_tr_b16 v[46:47], v124
	s_waitcnt lgkmcnt(2)
	v_mfma_f32_32x32x16_bf16 v[2:17], v[52:55], v[48:51], v[2:17]
	ds_read_b64_tr_b16 v[48:49], v123
	ds_read_b64_tr_b16 v[50:51], v122
	s_waitcnt lgkmcnt(2)
	v_mfma_f32_32x32x16_bf16 v[18:33], v[44:47], v[38:41], v[18:33]
	ds_read_b64_tr_b16 v[44:45], v119
	ds_read_b64_tr_b16 v[46:47], v118
	s_waitcnt lgkmcnt(2)
	v_mfma_f32_32x32x16_bf16 v[2:17], v[48:51], v[38:41], v[2:17]
	ds_read_b64_tr_b16 v[38:39], v121
	ds_read_b64_tr_b16 v[40:41], v120
	s_waitcnt lgkmcnt(0)
	v_mfma_f32_32x32x16_bf16 v[18:33], v[38:41], v[34:37], v[18:33]
	v_mfma_f32_32x32x16_bf16 v[2:17], v[44:47], v[34:37], v[2:17]

; #define LAS __attribute__((address_space(3)))
; #define WG_BAR() do { asm volatile("s_waitcnt lgkmcnt(0)" ::: "memory"); __builtin_amdgcn_s_barrier(); asm volatile("" ::: "memory"); } while (0)
; #define ATT_DMA(t) do { const int t_ = (t) < NS ? (t) : NS - 1; const size_t ro_ = (size_t)TILE_ROW(t_) * ZC; LAS unsigned char* d_ = dk0 + ((t) % ATT_NB) * KV_BUF; \
;         __builtin_amdgcn_global_load_lds((const unsigned*)(gk + ro_), (LAS unsigned*)d_, 16, 0, 0); __builtin_amdgcn_global_load_lds((const unsigned*)(gv + ro_), (LAS unsigned*)(d_ + KV_TILE), 16, 0, 0); } while (0)
; template <bool ISB>
; __device__ __forceinline__ void attn_wg_item(Frame& F, int l, int idx) {
;     ...
;     for (int s = 0; s < NS; ++s) {
;         ATT_DMA(s + ATT_D);
;         asm volatile("s_waitcnt vmcnt(8)" ::: "memory");
;         WG_BAR();
;         LAS unsigned char* cur = ring + (s % ATT_NB) * KV_BUF;
;         if (s >= nloc) { ScorePlain sf; attn_step(st, qf, cur, cur + KV_TILE, lane, sf); }
;         else if (!ISB) { int dkv = krow_base + 64 * s - qrow0; asm volatile("" : "+v"(dkv)); ScoreWin sf{dkv}; attn_step(st, qf, cur, cur + KV_TILE, lane, sf); }
;         else { const int gr = r0 + (w >> 1); int kr0 = gr - 4; kr0 = kr0 < 0 ? 0 : (kr0 > 120 ? 120 : kr0); const int kr = kmin + s;
;             if (kr >= kr0 && kr < kr0 + 8) { const int cq = 32 * (w & 1) + (lane & 31), hh = lane >> 5; int cs = cq - 8; cs = cs < 0 ? 0 : (cs > 48 ? 48 : cs);
;                 ScoreNb sf{(LAS unsigned char*)(tab + 64) + ((kr - gr + 7) * 31 + 15 - cq + 4 * hh) * 4, cs - 4 * hh}; attn_step(st, qf, cur, cur + KV_TILE, lane, sf); } }
;     }
.Lb623_exit:
	v_mov_b32_e32 v140, v131
	v_mov_b32_e32 v141, v130
	s_nop 8
	v_mov_b32_e32 v34, v18
	v_mov_b32_e32 v35, v19
	v_mov_b32_e32 v36, v20
	v_mov_b32_e32 v37, v21
	v_mov_b32_e32 v38, v22
	v_mov_b32_e32 v39, v23
	v_mov_b32_e32 v40, v24
	v_mov_b32_e32 v41, v25
	v_mov_b32_e32 v42, v26
	v_mov_b32_e32 v43, v27
	v_mov_b32_e32 v44, v28
	v_mov_b32_e32 v45, v29
	v_mov_b32_e32 v46, v30
	v_mov_b32_e32 v47, v31
	v_mov_b32_e32 v48, v32
	v_mov_b32_e32 v49, v33
	v_mov_b32_e32 v50, v2
	v_mov_b32_e32 v51, v3
	v_mov_b32_e32 v52, v4
	v_mov_b32_e32 v53, v5
	v_mov_b32_e32 v54, v6
	v_mov_b32_e32 v55, v7
	v_mov_b32_e32 v56, v8
	v_mov_b32_e32 v57, v9
	v_mov_b32_e32 v58, v10
	v_mov_b32_e32 v59, v11
	v_mov_b32_e32 v60, v12
	v_mov_b32_e32 v61, v13
	v_mov_b32_e32 v62, v14
	v_mov_b32_e32 v63, v15
	v_mov_b32_e32 v64, v16
	v_mov_b32_e32 v65, v17
	s_branch .LBB0_626
	s_nop 0
	s_nop 0
	s_nop 0
	s_nop 0
	s_nop 0
	s_nop 0
	s_nop 0
	s_nop 0
	s_nop 0
	s_nop 0
	s_nop 0
	s_nop 0
	s_nop 0
	s_nop 0
	s_nop 0
